# double-phase K-loop + epilogue-interval alignment extended to g2, gin and gout loops
# speedup vs baseline: 1.0270x; 1.0192x over previous
.LBB0_120:
	s_and_b64 vcc, exec, s[38:39]
	s_cbranch_vccnz .LBB0_164
	v_bfe_i32 v1, v141, 27, 1
	v_lshlrev_b32_e32 v3, 4, v141
	v_lshrrev_b32_e32 v1, 22, v1
	v_ashrrev_i32_e32 v0, 31, v141
	v_add_u32_e32 v1, v3, v1
	v_lshrrev_b32_e32 v0, 26, v0
	v_and_b32_e32 v1, 0xfffffc00, v1
	v_add_u32_e32 v0, v141, v0
	v_sub_u32_e32 v1, v3, v1
	v_ashrrev_i32_e32 v0, 6, v0
	v_lshrrev_b32_e32 v2, 4, v1
	v_bitop3_b32 v2, v2, v1, 32 bitop3:0x6c
	v_lshlrev_b32_e32 v1, 3, v0
	v_and_b32_e32 v4, -16, v1
	v_ashrrev_i32_e32 v1, 31, v2
	v_lshrrev_b32_e32 v1, 26, v1
	v_add_u32_e32 v5, v2, v1
	v_ashrrev_i32_e32 v1, 6, v5
	v_and_b32_e32 v5, 0xc0, v5
	v_sub_u32_e32 v2, v2, v5
	s_waitcnt lgkmcnt(0)
	v_mov_b32_e32 v9, 1
	v_lshlrev_b32_e32 v6, 5, v0
	v_ashrrev_i16_sdwa v2, v9, sext(v2) dst_sel:DWORD dst_unused:UNUSED_PAD src0_sel:DWORD src1_sel:BYTE_0
	v_and_b32_e32 v6, 32, v6
	v_bfe_i32 v2, v2, 0, 16
	v_add_u32_e32 v4, v1, v4
	v_and_b32_e32 v8, 3, v1
	s_mov_b32 s1, 0x1fffe0
	v_add_lshl_u32 v6, v6, v2, 1
	v_lshlrev_b32_e32 v5, 1, v4
	v_lshrrev_b32_e32 v7, 2, v4
	v_and_or_b32 v8, v4, s1, v8
	v_lshl_add_u32 v144, v4, 11, v6
	v_add_u32_e32 v4, 0x2000, v3
	v_ashrrev_i32_e32 v3, 31, v4
	v_lshrrev_b32_e32 v3, 22, v3
	v_and_b32_e32 v5, 24, v5
	v_and_b32_e32 v7, 4, v7
	v_add_u32_e32 v3, v4, v3
	v_or3_b32 v5, v8, v7, v5
	v_ashrrev_i32_e32 v3, 10, v3
	v_lshl_add_u32 v128, v5, 11, v6
	v_mul_i32_i24_e32 v5, 0x400, v3
	v_sub_u32_e32 v4, v4, v5
	v_lshrrev_b32_e32 v5, 4, v4
	v_bitop3_b32 v5, v5, v4, 32 bitop3:0x6c
	v_lshlrev_b32_e32 v4, 3, v3
	v_and_b32_e32 v6, -16, v4
	v_ashrrev_i32_e32 v4, 31, v5
	v_lshrrev_b32_e32 v4, 26, v4
	v_add_u32_e32 v7, v5, v4
	v_ashrrev_i32_e32 v4, 6, v7
	s_ashr_i32 s0, s50, 6
	v_add_u32_e32 v6, v4, v6
	v_and_b32_e32 v10, 3, v4
	v_and_or_b32 v10, v6, s1, v10
	s_ashr_i32 s1, s50, 8
	s_lshl_b32 s5, s0, 10
	s_lshl_b32 s4, s56, 21
	v_readlane_b32 s12, v252, 33
	v_readlane_b32 s13, v252, 34
	s_add_u32 s16, s12, s4
	s_addc_u32 s17, s13, 0
	s_ashr_i32 s41, s40, 31
	s_ashr_i32 s9, s8, 31
	v_and_b32_e32 v7, 0xc0, v7
	s_lshl_b64 s[12:13], s[40:41], 19
	s_lshl_b64 s[14:15], s[8:9], 19
	v_sub_u32_e32 v5, v5, v7
	s_add_u32 s14, s16, s14
	v_lshlrev_b32_e32 v8, 5, v3
	v_ashrrev_i16_sdwa v5, v9, sext(v5) dst_sel:DWORD dst_unused:UNUSED_PAD src0_sel:DWORD src1_sel:BYTE_0
	v_lshlrev_b32_e32 v7, 1, v6
	v_lshrrev_b32_e32 v9, 2, v6
	s_addc_u32 s15, s17, s15
	s_add_i32 s9, s5, 16
	v_and_b32_e32 v8, 32, v8
	v_bfe_i32 v5, v5, 0, 16
	v_and_b32_e32 v7, 24, v7
	v_and_b32_e32 v9, 4, v9
	s_add_i32 m0, s9, 0x10000
	v_or3_b32 v7, v10, v9, v7
	v_add_lshl_u32 v8, v8, v5, 1
	global_load_lds_dwordx4 v128, s[14:15]
	s_add_i32 m0, s9, 0x12000
	v_lshl_add_u32 v148, v7, 11, v8
	s_add_u32 s18, s6, s12
	global_load_lds_dwordx4 v148, s[14:15]
	s_addc_u32 s19, s7, s13
	s_mov_b32 m0, s9
	s_add_i32 s36, s9, 0x2000
	v_lshl_add_u32 v146, v6, 11, v8
	global_load_lds_dwordx4 v144, s[18:19]
	s_mov_b32 m0, s36
	s_add_u32 s12, s14, 0x40000
	global_load_lds_dwordx4 v146, s[18:19]
	s_addc_u32 s13, s15, 0
	s_add_i32 m0, s9, 0x14000
	s_nop 0
	global_load_lds_dwordx4 v128, s[12:13]
	s_add_i32 m0, s9, 0x16000
	s_nop 0
	global_load_lds_dwordx4 v148, s[12:13]
	s_add_u32 s12, s18, 0x40000
	s_addc_u32 s13, s19, 0
	s_add_i32 s37, s9, 0x4000
	s_mov_b32 m0, s37
	s_add_i32 s46, s9, 0x6000
	global_load_lds_dwordx4 v144, s[12:13]
	s_mov_b32 m0, s46
	s_cmp_lg_u32 s1, 1
	global_load_lds_dwordx4 v146, s[12:13]
.LBB0_123:
	v_lshrrev_b32_e32 v15, 1, v141
	v_and_b32_e32 v15, 24, v15
	v_lshl_add_u64 v[6:7], s[14:15], 0, v[128:129]
	v_mov_b32_e32 v149, v129
	v_and_b32_e32 v14, 15, v141
	v_lshlrev_b32_e32 v16, 1, v15
	s_lshl_b32 s0, s0, 5
	v_lshl_add_u64 v[8:9], s[14:15], 0, v[148:149]
	v_mov_b32_e32 v145, v129
	v_lshl_or_b32 v143, s1, 6, v14
	v_lshl_or_b32 v14, v14, 6, v16
	v_lshlrev_b32_e32 v16, 2, v141
	s_and_b32 s4, s0, 0x60
	s_add_i32 m0, s9, 0x18000
	v_lshl_add_u64 v[6:7], v[6:7], 0, s[28:29]
	v_lshl_add_u64 v[10:11], s[18:19], 0, v[144:145]
	v_mov_b32_e32 v147, v129
	s_lshl_b32 s1, s1, 13
	v_and_b32_e32 v16, 32, v16
	s_lshl_b32 s0, s4, 7
	s_waitcnt vmcnt(4)
	s_barrier
	global_load_lds_dwordx4 v[6:7], off
	v_lshl_add_u64 v[6:7], v[8:9], 0, s[28:29]
	s_add_i32 m0, s9, 0x1a000
	s_add_i32 s47, s9, 0x8000
	s_add_i32 s92, s9, 0xa000
	v_lshl_add_u64 v[12:13], s[18:19], 0, v[146:147]
	v_bitop3_b32 v160, s0, v14, v16 bitop3:0xf6
	global_load_lds_dwordx4 v[6:7], off
	v_lshl_add_u64 v[6:7], v[10:11], 0, s[28:29]
	s_mov_b32 m0, s47
	s_add_u32 s0, s14, 0x40080
	v_bitop3_b32 v17, v14, s1, v16 bitop3:0xde
	global_load_lds_dwordx4 v[6:7], off
	v_lshl_add_u64 v[6:7], v[12:13], 0, s[28:29]
	s_mov_b32 m0, s92
	s_addc_u32 s1, s15, 0
	global_load_lds_dwordx4 v[6:7], off
	s_add_i32 m0, s9, 0x1c000
	v_lshl_add_u64 v[6:7], s[0:1], 0, v[128:129]
	global_load_lds_dwordx4 v[6:7], off
	v_lshl_add_u64 v[6:7], s[0:1], 0, v[148:149]
	s_add_i32 m0, s9, 0x1e000
	v_or_b32_e32 v161, s4, v15
	global_load_lds_dwordx4 v[6:7], off
	v_lshlrev_b32_e32 v6, 14, v0
	v_and_b32_e32 v6, 0xffff8000, v6
	v_lshl_add_u32 v1, v1, 11, v6
	v_and_b32_e32 v0, 1, v0
	v_lshl_or_b32 v0, v0, 6, v1
	v_lshl_add_u32 v150, v2, 1, v0
	v_lshlrev_b32_e32 v0, 14, v3
	v_and_b32_e32 v0, 0xffff8000, v0
	s_waitcnt vmcnt(6)
	v_lshl_add_u32 v0, v4, 11, v0
	v_and_b32_e32 v1, 1, v3
	v_lshl_or_b32 v0, v1, 6, v0
	v_mov_b32_e32 v151, v129
	v_lshl_add_u32 v152, v5, 1, v0
	v_mov_b32_e32 v153, v129
	s_mov_b32 s4, 0
	v_add_u32_e32 v162, 16, v17
	s_barrier
	s_branch .LBB0_125

.LBB0_127:
	s_ashr_i32 s13, s12, 31
	s_lshl_b64 s[0:1], s[12:13], 19
	s_add_u32 s42, s6, s0
	v_cmp_lt_i64_e32 vcc, s[34:35], v[236:237]
	s_addc_u32 s43, s7, s1
	s_and_b64 s[0:1], vcc, exec
	s_cselect_b32 s0, s43, s19
	s_cselect_b32 s1, s42, s18
	s_ashr_i32 s31, s30, 31
	s_lshl_b64 s[24:25], s[30:31], 19
	s_add_u32 s44, s16, s24
	s_addc_u32 s45, s17, s25
	s_and_b64 s[24:25], vcc, exec
	s_cselect_b32 s13, s45, s15
	s_cselect_b32 s24, s44, s14
	s_add_u32 vcc_lo, s18, 0x40080
	s_addc_u32 vcc_hi, s19, 0
	s_add_u32 s25, s14, 0x100
	v_mov_b32_e32 v0, 0
	s_addc_u32 s31, s15, 0
	s_mov_b32 s34, -2
	v_mov_b32_e32 v1, v0
	v_mov_b32_e32 v2, v0
	v_mov_b32_e32 v3, v0
	v_mov_b32_e32 v4, v0
	v_mov_b32_e32 v5, v0
	v_mov_b32_e32 v6, v0
	v_mov_b32_e32 v7, v0
	v_mov_b32_e32 v16, v0
	v_mov_b32_e32 v17, v0
	v_mov_b32_e32 v18, v0
	v_mov_b32_e32 v19, v0
	v_mov_b32_e32 v20, v0
	v_mov_b32_e32 v21, v0
	v_mov_b32_e32 v22, v0
	v_mov_b32_e32 v23, v0
	v_mov_b32_e32 v32, v0
	v_mov_b32_e32 v33, v0
	v_mov_b32_e32 v34, v0
	v_mov_b32_e32 v35, v0
	v_mov_b32_e32 v36, v0
	v_mov_b32_e32 v37, v0
	v_mov_b32_e32 v38, v0
	v_mov_b32_e32 v39, v0
	v_mov_b32_e32 v48, v0
	v_mov_b32_e32 v49, v0
	v_mov_b32_e32 v50, v0
	v_mov_b32_e32 v51, v0
	v_mov_b32_e32 v52, v0
	v_mov_b32_e32 v53, v0
	v_mov_b32_e32 v54, v0
	v_mov_b32_e32 v55, v0
	v_mov_b32_e32 v8, v0
	v_mov_b32_e32 v9, v0
	v_mov_b32_e32 v10, v0
	v_mov_b32_e32 v11, v0
	v_mov_b32_e32 v12, v0
	v_mov_b32_e32 v13, v0
	v_mov_b32_e32 v14, v0
	v_mov_b32_e32 v15, v0
	v_mov_b32_e32 v24, v0
	v_mov_b32_e32 v25, v0
	v_mov_b32_e32 v26, v0
	v_mov_b32_e32 v27, v0
	v_mov_b32_e32 v28, v0
	v_mov_b32_e32 v29, v0
	v_mov_b32_e32 v30, v0
	v_mov_b32_e32 v31, v0
	v_mov_b32_e32 v40, v0
	v_mov_b32_e32 v41, v0
	v_mov_b32_e32 v42, v0
	v_mov_b32_e32 v43, v0
	v_mov_b32_e32 v44, v0
	v_mov_b32_e32 v45, v0
	v_mov_b32_e32 v46, v0
	v_mov_b32_e32 v47, v0
	v_mov_b32_e32 v56, v0
	v_mov_b32_e32 v57, v0
	v_mov_b32_e32 v58, v0
	v_mov_b32_e32 v59, v0
	v_mov_b32_e32 v60, v0
	v_mov_b32_e32 v61, v0
	v_mov_b32_e32 v62, v0
	v_mov_b32_e32 v63, v0
	v_mov_b32_e32 v64, v0
	v_mov_b32_e32 v65, v0
	v_mov_b32_e32 v66, v0
	v_mov_b32_e32 v67, v0
	v_mov_b32_e32 v68, v0
	v_mov_b32_e32 v69, v0
	v_mov_b32_e32 v70, v0
	v_mov_b32_e32 v71, v0
	v_mov_b32_e32 v80, v0
	v_mov_b32_e32 v81, v0
	v_mov_b32_e32 v82, v0
	v_mov_b32_e32 v83, v0
	v_mov_b32_e32 v84, v0
	v_mov_b32_e32 v85, v0
	v_mov_b32_e32 v86, v0
	v_mov_b32_e32 v87, v0
	v_mov_b32_e32 v96, v0
	v_mov_b32_e32 v97, v0
	v_mov_b32_e32 v98, v0
	v_mov_b32_e32 v99, v0
	v_mov_b32_e32 v100, v0
	v_mov_b32_e32 v101, v0
	v_mov_b32_e32 v102, v0
	v_mov_b32_e32 v103, v0
	v_mov_b32_e32 v112, v0
	v_mov_b32_e32 v113, v0
	v_mov_b32_e32 v114, v0
	v_mov_b32_e32 v115, v0
	v_mov_b32_e32 v116, v0
	v_mov_b32_e32 v117, v0
	v_mov_b32_e32 v118, v0
	v_mov_b32_e32 v119, v0
	v_mov_b32_e32 v72, v0
	v_mov_b32_e32 v73, v0
	v_mov_b32_e32 v74, v0
	v_mov_b32_e32 v75, v0
	v_mov_b32_e32 v76, v0
	v_mov_b32_e32 v77, v0
	v_mov_b32_e32 v78, v0
	v_mov_b32_e32 v79, v0
	v_mov_b32_e32 v88, v0
	v_mov_b32_e32 v89, v0
	v_mov_b32_e32 v90, v0
	v_mov_b32_e32 v91, v0
	v_mov_b32_e32 v92, v0
	v_mov_b32_e32 v93, v0
	v_mov_b32_e32 v94, v0
	v_mov_b32_e32 v95, v0
	v_mov_b32_e32 v104, v0
	v_mov_b32_e32 v105, v0
	v_mov_b32_e32 v106, v0
	v_mov_b32_e32 v107, v0
	v_mov_b32_e32 v108, v0
	v_mov_b32_e32 v109, v0
	v_mov_b32_e32 v110, v0
	v_mov_b32_e32 v111, v0
	v_mov_b32_e32 v120, v0
	v_mov_b32_e32 v121, v0
	v_mov_b32_e32 v122, v0
	v_mov_b32_e32 v123, v0
	v_mov_b32_e32 v124, v0
	v_mov_b32_e32 v125, v0
	v_mov_b32_e32 v126, v0
	v_mov_b32_e32 v127, v0
	s_cmpk_gt_u32 s50, 0xff
	s_cbranch_scc0 .Lgout_enter
	s_barrier
.Lgout_enter:
.LBB0_128:
	s_add_u32 s14, vcc_lo, 0xfffc0080
	s_addc_u32 s15, vcc_hi, -1
	s_add_i32 s20, 16, 0x10000
	v_add_u32_e32 v130, s20, v160
	ds_read_b128 v[154:157], v130
	ds_read_b128 v[164:167], v130 offset:1024
	ds_read_b128 v[168:171], v130 offset:2048
	ds_read_b128 v[172:175], v130 offset:3072
	s_cmp_eq_u32 s34, 12
	s_cselect_b32 s19, s0, s15
	s_cselect_b32 s18, s1, s14
	s_cselect_b32 s15, s13, s31
	s_cselect_b32 s14, s24, s25
	v_lshl_add_u64 v[130:131], vcc, 0, v[150:151]
	s_add_i32 m0, s9, 0xc000
	ds_read_b128 v[176:179], v162
	ds_read_b128 v[180:183], v162 offset:1024
	ds_read_b128 v[184:187], v162 offset:2048
	ds_read_b128 v[188:191], v162 offset:3072
	ds_read_b128 v[192:195], v162 offset:4096
	ds_read_b128 v[196:199], v162 offset:5120
	ds_read_b128 v[200:203], v162 offset:6144
	ds_read_b128 v[204:207], v162 offset:7168
	global_load_lds_dwordx4 v[130:131], off
	v_lshl_add_u64 v[130:131], vcc, 0, v[152:153]
	s_add_i32 m0, s9, 0xe000
	s_nop 0
	global_load_lds_dwordx4 v[130:131], off
	s_add_i32 s35, 16, 0x14000
	v_add_u32_e32 v130, s35, v160
	ds_read_b128 v[208:211], v130
	ds_read_b128 v[212:215], v130 offset:1024
	ds_read_b128 v[216:219], v130 offset:2048
	ds_read_b128 v[220:223], v130 offset:3072
	s_waitcnt vmcnt(8) lgkmcnt(0)
	s_barrier
	s_setprio 1
	v_mfma_f32_16x16x32_bf16 v[124:127], v[154:157], v[176:179], v[124:127]
	v_mfma_f32_16x16x32_bf16 v[120:123], v[168:171], v[176:179], v[120:123]
	v_mfma_f32_16x16x32_bf16 v[108:111], v[154:157], v[184:187], v[108:111]
	v_mfma_f32_16x16x32_bf16 v[104:107], v[168:171], v[184:187], v[104:107]
	v_mfma_f32_16x16x32_bf16 v[92:95], v[154:157], v[192:195], v[92:95]
	v_mfma_f32_16x16x32_bf16 v[88:91], v[168:171], v[192:195], v[88:91]
	v_mfma_f32_16x16x32_bf16 v[76:79], v[154:157], v[200:203], v[76:79]
	v_mfma_f32_16x16x32_bf16 v[72:75], v[168:171], v[200:203], v[72:75]
	v_mfma_f32_16x16x32_bf16 v[124:127], v[164:167], v[180:183], v[124:127]
	v_mfma_f32_16x16x32_bf16 v[120:123], v[172:175], v[180:183], v[120:123]
	v_mfma_f32_16x16x32_bf16 v[108:111], v[164:167], v[188:191], v[108:111]
	v_mfma_f32_16x16x32_bf16 v[104:107], v[172:175], v[188:191], v[104:107]
	v_mfma_f32_16x16x32_bf16 v[92:95], v[164:167], v[196:199], v[92:95]
	v_mfma_f32_16x16x32_bf16 v[88:91], v[172:175], v[196:199], v[88:91]
	v_mfma_f32_16x16x32_bf16 v[76:79], v[164:167], v[204:207], v[76:79]
	v_mfma_f32_16x16x32_bf16 v[72:75], v[172:175], v[204:207], v[72:75]
	v_mfma_f32_16x16x32_bf16 v[116:119], v[208:211], v[176:179], v[116:119]
	v_mfma_f32_16x16x32_bf16 v[112:115], v[216:219], v[176:179], v[112:115]
	v_mfma_f32_16x16x32_bf16 v[100:103], v[208:211], v[184:187], v[100:103]
	v_mfma_f32_16x16x32_bf16 v[96:99], v[216:219], v[184:187], v[96:99]
	v_mfma_f32_16x16x32_bf16 v[84:87], v[208:211], v[192:195], v[84:87]
	v_mfma_f32_16x16x32_bf16 v[80:83], v[216:219], v[192:195], v[80:83]
	v_mfma_f32_16x16x32_bf16 v[68:71], v[208:211], v[200:203], v[68:71]
	v_mfma_f32_16x16x32_bf16 v[64:67], v[216:219], v[200:203], v[64:67]
	v_mfma_f32_16x16x32_bf16 v[116:119], v[212:215], v[180:183], v[116:119]
	v_mfma_f32_16x16x32_bf16 v[112:115], v[220:223], v[180:183], v[112:115]
	v_mfma_f32_16x16x32_bf16 v[100:103], v[212:215], v[188:191], v[100:103]
	v_mfma_f32_16x16x32_bf16 v[96:99], v[220:223], v[188:191], v[96:99]
	v_mfma_f32_16x16x32_bf16 v[84:87], v[212:215], v[196:199], v[84:87]
	v_mfma_f32_16x16x32_bf16 v[80:83], v[220:223], v[196:199], v[80:83]
	v_mfma_f32_16x16x32_bf16 v[68:71], v[212:215], v[204:207], v[68:71]
	v_mfma_f32_16x16x32_bf16 v[64:67], v[220:223], v[204:207], v[64:67]
	s_setprio 0
	s_barrier
	ds_read_b128 v[176:179], v162 offset:16384
	ds_read_b128 v[180:183], v162 offset:17408
	ds_read_b128 v[184:187], v162 offset:18432
	ds_read_b128 v[188:191], v162 offset:19456
	ds_read_b128 v[192:195], v162 offset:20480
	ds_read_b128 v[196:199], v162 offset:21504
	ds_read_b128 v[200:203], v162 offset:22528
	ds_read_b128 v[204:207], v162 offset:23552
	s_add_i32 s20, s20, s5
	v_lshl_add_u64 v[130:131], s[14:15], 0, v[128:129]
	s_mov_b32 m0, s20
	v_lshl_add_u64 v[132:133], s[14:15], 0, v[148:149]
	global_load_lds_dwordx4 v[130:131], off
	s_add_i32 m0, s20, 0x2000
	s_nop 0
	global_load_lds_dwordx4 v[132:133], off
	s_mov_b32 m0, s9
	v_lshl_add_u64 v[134:135], s[18:19], 0, v[144:145]
	global_load_lds_dwordx4 v[134:135], off
	v_lshl_add_u64 v[136:137], s[18:19], 0, v[146:147]
	s_mov_b32 m0, s36
	s_nop 0
	global_load_lds_dwordx4 v[136:137], off
	s_add_u32 s48, s14, 0x40000
	s_addc_u32 s49, s15, 0
	s_add_i32 s20, s35, s5
	v_lshl_add_u64 v[138:139], s[48:49], 0, v[128:129]
	s_mov_b32 m0, s20
	s_nop 0
	global_load_lds_dwordx4 v[138:139], off
	v_lshl_add_u64 v[138:139], s[48:49], 0, v[148:149]
	s_add_i32 m0, s20, 0x2000
	s_nop 0
	global_load_lds_dwordx4 v[138:139], off
	s_waitcnt vmcnt(8) lgkmcnt(0)
	s_barrier
	s_setprio 1
	v_mfma_f32_16x16x32_bf16 v[60:63], v[154:157], v[176:179], v[60:63]
	v_mfma_f32_16x16x32_bf16 v[56:59], v[168:171], v[176:179], v[56:59]
	v_mfma_f32_16x16x32_bf16 v[44:47], v[154:157], v[184:187], v[44:47]
	v_mfma_f32_16x16x32_bf16 v[40:43], v[168:171], v[184:187], v[40:43]
	v_mfma_f32_16x16x32_bf16 v[28:31], v[154:157], v[192:195], v[28:31]
	v_mfma_f32_16x16x32_bf16 v[24:27], v[168:171], v[192:195], v[24:27]
	v_mfma_f32_16x16x32_bf16 v[12:15], v[154:157], v[200:203], v[12:15]
	v_mfma_f32_16x16x32_bf16 v[8:11], v[168:171], v[200:203], v[8:11]
	v_mfma_f32_16x16x32_bf16 v[60:63], v[164:167], v[180:183], v[60:63]
	v_mfma_f32_16x16x32_bf16 v[56:59], v[172:175], v[180:183], v[56:59]
	v_mfma_f32_16x16x32_bf16 v[44:47], v[164:167], v[188:191], v[44:47]
	v_mfma_f32_16x16x32_bf16 v[40:43], v[172:175], v[188:191], v[40:43]
	v_mfma_f32_16x16x32_bf16 v[28:31], v[164:167], v[196:199], v[28:31]
	v_mfma_f32_16x16x32_bf16 v[24:27], v[172:175], v[196:199], v[24:27]
	v_mfma_f32_16x16x32_bf16 v[12:15], v[164:167], v[204:207], v[12:15]
	v_mfma_f32_16x16x32_bf16 v[8:11], v[172:175], v[204:207], v[8:11]
	v_mfma_f32_16x16x32_bf16 v[52:55], v[208:211], v[176:179], v[52:55]
	v_mfma_f32_16x16x32_bf16 v[48:51], v[216:219], v[176:179], v[48:51]
	v_mfma_f32_16x16x32_bf16 v[36:39], v[208:211], v[184:187], v[36:39]
	v_mfma_f32_16x16x32_bf16 v[32:35], v[216:219], v[184:187], v[32:35]
	v_mfma_f32_16x16x32_bf16 v[20:23], v[208:211], v[192:195], v[20:23]
	v_mfma_f32_16x16x32_bf16 v[16:19], v[216:219], v[192:195], v[16:19]
	v_mfma_f32_16x16x32_bf16 v[4:7], v[208:211], v[200:203], v[4:7]
	v_mfma_f32_16x16x32_bf16 v[0:3], v[216:219], v[200:203], v[0:3]
	v_mfma_f32_16x16x32_bf16 v[52:55], v[212:215], v[180:183], v[52:55]
	v_mfma_f32_16x16x32_bf16 v[48:51], v[220:223], v[180:183], v[48:51]
	v_mfma_f32_16x16x32_bf16 v[36:39], v[212:215], v[188:191], v[36:39]
	v_mfma_f32_16x16x32_bf16 v[32:35], v[220:223], v[188:191], v[32:35]
	v_mfma_f32_16x16x32_bf16 v[20:23], v[212:215], v[196:199], v[20:23]
	v_mfma_f32_16x16x32_bf16 v[16:19], v[220:223], v[196:199], v[16:19]
	v_mfma_f32_16x16x32_bf16 v[4:7], v[212:215], v[204:207], v[4:7]
	v_mfma_f32_16x16x32_bf16 v[0:3], v[220:223], v[204:207], v[0:3]
	s_setprio 0
	s_add_i32 s20, 16, 0x18000
	v_add_u32_e32 v138, s20, v160
	s_barrier
	ds_read_b128 v[154:157], v138
	ds_read_b128 v[164:167], v138 offset:1024
	ds_read_b128 v[168:171], v138 offset:2048
	ds_read_b128 v[172:175], v138 offset:3072
	s_add_u32 s18, s18, 0x40000
	s_addc_u32 s19, s19, 0
	s_mov_b32 m0, s37
	v_lshl_add_u64 v[158:159], s[18:19], 0, v[144:145]
	ds_read_b128 v[176:179], v162 offset:32768
	ds_read_b128 v[180:183], v162 offset:33792
	ds_read_b128 v[184:187], v162 offset:34816
	ds_read_b128 v[188:191], v162 offset:35840
	ds_read_b128 v[192:195], v162 offset:36864
	ds_read_b128 v[196:199], v162 offset:37888
	ds_read_b128 v[200:203], v162 offset:38912
	ds_read_b128 v[204:207], v162 offset:39936
	global_load_lds_dwordx4 v[158:159], off
	v_lshl_add_u64 v[158:159], s[18:19], 0, v[146:147]
	s_mov_b32 m0, s46
	s_nop 0
	global_load_lds_dwordx4 v[158:159], off
	s_add_i32 s18, 16, 0x1c000
	v_add_u32_e32 v138, s18, v160
	ds_read_b128 v[208:211], v138
	ds_read_b128 v[212:215], v138 offset:1024
	ds_read_b128 v[216:219], v138 offset:2048
	ds_read_b128 v[220:223], v138 offset:3072
	s_waitcnt vmcnt(8) lgkmcnt(0)
	s_barrier
	s_setprio 1
	v_mfma_f32_16x16x32_bf16 v[124:127], v[154:157], v[176:179], v[124:127]
	v_mfma_f32_16x16x32_bf16 v[120:123], v[168:171], v[176:179], v[120:123]
	v_mfma_f32_16x16x32_bf16 v[108:111], v[154:157], v[184:187], v[108:111]
	v_mfma_f32_16x16x32_bf16 v[104:107], v[168:171], v[184:187], v[104:107]
	v_mfma_f32_16x16x32_bf16 v[92:95], v[154:157], v[192:195], v[92:95]
	v_mfma_f32_16x16x32_bf16 v[88:91], v[168:171], v[192:195], v[88:91]
	v_mfma_f32_16x16x32_bf16 v[76:79], v[154:157], v[200:203], v[76:79]
	v_mfma_f32_16x16x32_bf16 v[72:75], v[168:171], v[200:203], v[72:75]
	v_mfma_f32_16x16x32_bf16 v[124:127], v[164:167], v[180:183], v[124:127]
	v_mfma_f32_16x16x32_bf16 v[120:123], v[172:175], v[180:183], v[120:123]
	v_mfma_f32_16x16x32_bf16 v[108:111], v[164:167], v[188:191], v[108:111]
	v_mfma_f32_16x16x32_bf16 v[104:107], v[172:175], v[188:191], v[104:107]
	v_mfma_f32_16x16x32_bf16 v[92:95], v[164:167], v[196:199], v[92:95]
	v_mfma_f32_16x16x32_bf16 v[88:91], v[172:175], v[196:199], v[88:91]
	v_mfma_f32_16x16x32_bf16 v[76:79], v[164:167], v[204:207], v[76:79]
	v_mfma_f32_16x16x32_bf16 v[72:75], v[172:175], v[204:207], v[72:75]
	v_mfma_f32_16x16x32_bf16 v[116:119], v[208:211], v[176:179], v[116:119]
	v_mfma_f32_16x16x32_bf16 v[112:115], v[216:219], v[176:179], v[112:115]
	v_mfma_f32_16x16x32_bf16 v[100:103], v[208:211], v[184:187], v[100:103]
	v_mfma_f32_16x16x32_bf16 v[96:99], v[216:219], v[184:187], v[96:99]
	v_mfma_f32_16x16x32_bf16 v[84:87], v[208:211], v[192:195], v[84:87]
	v_mfma_f32_16x16x32_bf16 v[80:83], v[216:219], v[192:195], v[80:83]
	v_mfma_f32_16x16x32_bf16 v[68:71], v[208:211], v[200:203], v[68:71]
	v_mfma_f32_16x16x32_bf16 v[64:67], v[216:219], v[200:203], v[64:67]
	v_mfma_f32_16x16x32_bf16 v[116:119], v[212:215], v[180:183], v[116:119]
	v_mfma_f32_16x16x32_bf16 v[112:115], v[220:223], v[180:183], v[112:115]
	v_mfma_f32_16x16x32_bf16 v[100:103], v[212:215], v[188:191], v[100:103]
	v_mfma_f32_16x16x32_bf16 v[96:99], v[220:223], v[188:191], v[96:99]
	v_mfma_f32_16x16x32_bf16 v[84:87], v[212:215], v[196:199], v[84:87]
	v_mfma_f32_16x16x32_bf16 v[80:83], v[220:223], v[196:199], v[80:83]
	v_mfma_f32_16x16x32_bf16 v[68:71], v[212:215], v[204:207], v[68:71]
	v_mfma_f32_16x16x32_bf16 v[64:67], v[220:223], v[204:207], v[64:67]
	s_setprio 0
	s_barrier
	ds_read_b128 v[176:179], v162 offset:49152
	ds_read_b128 v[180:183], v162 offset:50176
	ds_read_b128 v[184:187], v162 offset:51200
	ds_read_b128 v[188:191], v162 offset:52224
	ds_read_b128 v[192:195], v162 offset:53248
	ds_read_b128 v[196:199], v162 offset:54272
	ds_read_b128 v[200:203], v162 offset:55296
	ds_read_b128 v[204:207], v162 offset:56320
	s_add_i32 s19, s20, s5
	v_lshl_add_u64 v[130:131], v[130:131], 0, s[28:29]
	s_mov_b32 m0, s19
	s_nop 0
	global_load_lds_dwordx4 v[130:131], off
	v_lshl_add_u64 v[130:131], v[132:133], 0, s[28:29]
	s_add_i32 m0, s19, 0x2000
	s_nop 0
	global_load_lds_dwordx4 v[130:131], off
	s_mov_b32 m0, s47
	v_lshl_add_u64 v[130:131], v[134:135], 0, s[28:29]
	global_load_lds_dwordx4 v[130:131], off
	v_lshl_add_u64 v[130:131], v[136:137], 0, s[28:29]
	s_mov_b32 m0, s92
	s_nop 0
	global_load_lds_dwordx4 v[130:131], off
	s_add_u32 s14, s14, 0x40080
	s_addc_u32 s15, s15, 0
	s_add_i32 s18, s18, s5
	v_lshl_add_u64 v[130:131], s[14:15], 0, v[128:129]
	s_mov_b32 m0, s18
	s_nop 0
	global_load_lds_dwordx4 v[130:131], off
	v_lshl_add_u64 v[130:131], s[14:15], 0, v[148:149]
	s_add_i32 m0, s18, 0x2000
	s_nop 0
	global_load_lds_dwordx4 v[130:131], off
	s_waitcnt vmcnt(8) lgkmcnt(0)
	s_barrier
	s_setprio 1
	v_mfma_f32_16x16x32_bf16 v[60:63], v[154:157], v[176:179], v[60:63]
	v_mfma_f32_16x16x32_bf16 v[56:59], v[168:171], v[176:179], v[56:59]
	v_mfma_f32_16x16x32_bf16 v[44:47], v[154:157], v[184:187], v[44:47]
	v_mfma_f32_16x16x32_bf16 v[40:43], v[168:171], v[184:187], v[40:43]
	v_mfma_f32_16x16x32_bf16 v[28:31], v[154:157], v[192:195], v[28:31]
	v_mfma_f32_16x16x32_bf16 v[24:27], v[168:171], v[192:195], v[24:27]
	v_mfma_f32_16x16x32_bf16 v[12:15], v[154:157], v[200:203], v[12:15]
	v_mfma_f32_16x16x32_bf16 v[8:11], v[168:171], v[200:203], v[8:11]
	v_mfma_f32_16x16x32_bf16 v[60:63], v[164:167], v[180:183], v[60:63]
	v_mfma_f32_16x16x32_bf16 v[56:59], v[172:175], v[180:183], v[56:59]
	v_mfma_f32_16x16x32_bf16 v[44:47], v[164:167], v[188:191], v[44:47]
	v_mfma_f32_16x16x32_bf16 v[40:43], v[172:175], v[188:191], v[40:43]
	v_mfma_f32_16x16x32_bf16 v[28:31], v[164:167], v[196:199], v[28:31]
	v_mfma_f32_16x16x32_bf16 v[24:27], v[172:175], v[196:199], v[24:27]
	v_mfma_f32_16x16x32_bf16 v[12:15], v[164:167], v[204:207], v[12:15]
	v_mfma_f32_16x16x32_bf16 v[8:11], v[172:175], v[204:207], v[8:11]
	v_mfma_f32_16x16x32_bf16 v[52:55], v[208:211], v[176:179], v[52:55]
	v_mfma_f32_16x16x32_bf16 v[48:51], v[216:219], v[176:179], v[48:51]
	v_mfma_f32_16x16x32_bf16 v[36:39], v[208:211], v[184:187], v[36:39]
	v_mfma_f32_16x16x32_bf16 v[32:35], v[216:219], v[184:187], v[32:35]
	v_mfma_f32_16x16x32_bf16 v[20:23], v[208:211], v[192:195], v[20:23]
	v_mfma_f32_16x16x32_bf16 v[16:19], v[216:219], v[192:195], v[16:19]
	v_mfma_f32_16x16x32_bf16 v[4:7], v[208:211], v[200:203], v[4:7]
	v_mfma_f32_16x16x32_bf16 v[0:3], v[216:219], v[200:203], v[0:3]
	v_mfma_f32_16x16x32_bf16 v[52:55], v[212:215], v[180:183], v[52:55]
	v_mfma_f32_16x16x32_bf16 v[48:51], v[220:223], v[180:183], v[48:51]
	v_mfma_f32_16x16x32_bf16 v[36:39], v[212:215], v[188:191], v[36:39]
	v_mfma_f32_16x16x32_bf16 v[32:35], v[220:223], v[188:191], v[32:35]
	v_mfma_f32_16x16x32_bf16 v[20:23], v[212:215], v[196:199], v[20:23]
	v_mfma_f32_16x16x32_bf16 v[16:19], v[220:223], v[196:199], v[16:19]
	v_mfma_f32_16x16x32_bf16 v[4:7], v[212:215], v[204:207], v[4:7]
	v_mfma_f32_16x16x32_bf16 v[0:3], v[220:223], v[204:207], v[0:3]
	s_setprio 0
	s_add_i32 s34, s34, 2
	s_add_u32 vcc_lo, vcc_lo, 0x100
	s_addc_u32 vcc_hi, vcc_hi, 0
	s_add_u32 s25, s25, 0x100
	s_addc_u32 s31, s31, 0
	s_cmp_gt_u32 s34, 13
	s_cbranch_scc1 .Lgout_exit
	s_barrier
	s_branch .LBB0_128
.Lgout_exit:
	s_cmpk_gt_u32 s50, 0xff
	s_cbranch_scc1 .Lgout_epi
	s_barrier
.Lgout_epi:
	s_cmp_lt_i32 s8, 0
	s_cselect_b64 s[14:15], -1, 0
	s_cmp_gt_i32 s8, -1
	s_cbranch_scc1 .LBB0_131
	v_mul_f32_e32 v131, 0x3d372713, v120
	v_mul_f32_e32 v131, v120, v131
	v_fma_f32 v131, v120, v131, v120
	v_mul_f32_e32 v131, 0x3fcc422a, v131
	v_mul_f32_e32 v131, 0xbfb8aa3b, v131
	v_exp_f32_e32 v131, v131
	v_mul_f32_e32 v130, 0x3d372713, v124
	v_mul_f32_e32 v130, v124, v130
	v_fma_f32 v130, v124, v130, v124
	v_add_f32_e32 v131, 1.0, v131
	v_rcp_f32_e32 v132, v131
	v_mul_f32_e32 v131, 0x3d372713, v125
	v_mul_f32_e32 v131, v125, v131
	v_fma_f32 v131, v125, v131, v125
	v_mul_f32_e32 v130, 0x3fcc422a, v130
	v_mul_f32_e32 v131, 0x3fcc422a, v131
	v_mul_f32_e32 v130, 0xbfb8aa3b, v130
	v_mul_f32_e32 v131, 0xbfb8aa3b, v131
	v_mul_f32_e32 v135, 0x3d372713, v122
	v_exp_f32_e32 v130, v130
	v_exp_f32_e32 v131, v131
	v_mul_f32_e32 v135, v122, v135
	v_fma_f32 v135, v122, v135, v122
	v_mul_f32_e32 v135, 0x3fcc422a, v135
	v_mul_f32_e32 v135, 0xbfb8aa3b, v135
	v_add_f32_e32 v130, 1.0, v130
	v_add_f32_e32 v131, 1.0, v131
	v_exp_f32_e32 v135, v135
	v_rcp_f32_e32 v130, v130
	v_rcp_f32_e32 v131, v131
	v_mul_f32_e32 v133, 0x3d372713, v121
	v_add_f32_e32 v135, 1.0, v135
	v_mul_f32_e32 v134, 0x3d372713, v126
	v_rcp_f32_e32 v136, v135
	v_mul_f32_e32 v135, 0x3d372713, v127
	v_pk_mul_f32 v[124:125], v[124:125], v[130:131]
	v_mul_f32_e32 v130, 0x3d372713, v123
	v_mul_f32_e32 v133, v121, v133
	v_mul_f32_e32 v134, v126, v134
	v_mul_f32_e32 v135, v127, v135
	v_mul_f32_e32 v130, v123, v130
	v_fma_f32 v133, v121, v133, v121
	v_fma_f32 v134, v126, v134, v126
	v_fma_f32 v135, v127, v135, v127
	v_fma_f32 v130, v123, v130, v123
	v_mul_f32_e32 v133, 0x3fcc422a, v133
	v_mul_f32_e32 v134, 0x3fcc422a, v134
	v_mul_f32_e32 v135, 0x3fcc422a, v135
	v_mul_f32_e32 v130, 0x3fcc422a, v130
	v_mul_f32_e32 v133, 0xbfb8aa3b, v133
	v_mul_f32_e32 v134, 0xbfb8aa3b, v134
	v_mul_f32_e32 v135, 0xbfb8aa3b, v135
	v_mul_f32_e32 v130, 0xbfb8aa3b, v130
	v_exp_f32_e32 v133, v133
	v_exp_f32_e32 v134, v134
	v_exp_f32_e32 v135, v135
	v_exp_f32_e32 v130, v130
	v_add_f32_e32 v133, 1.0, v133
	v_add_f32_e32 v134, 1.0, v134
	v_add_f32_e32 v135, 1.0, v135
	v_add_f32_e32 v130, 1.0, v130
	v_rcp_f32_e32 v133, v133
	v_rcp_f32_e32 v134, v134
	v_rcp_f32_e32 v135, v135
	v_rcp_f32_e32 v137, v130
	v_pk_mul_f32 v[120:121], v[120:121], v[132:133]
	v_pk_mul_f32 v[126:127], v[126:127], v[134:135]
	v_pk_mul_f32 v[122:123], v[122:123], v[136:137]

.LBB0_161:
	s_waitcnt vmcnt(0)
.LBB0_163:
	s_movk_i32 s16, 0x300
	s_movk_i32 s17, 0x7f
	s_barrier

.LBB0_263:
	s_and_b64 vcc, exec, s[38:39]
	s_cbranch_vccnz .LBB0_307
	v_bfe_i32 v1, v141, 27, 1
	v_lshlrev_b32_e32 v3, 4, v141
	v_lshrrev_b32_e32 v1, 22, v1
	v_ashrrev_i32_e32 v0, 31, v141
	v_add_u32_e32 v1, v3, v1
	v_lshrrev_b32_e32 v0, 26, v0
	v_and_b32_e32 v1, 0xfffffc00, v1
	v_add_u32_e32 v0, v141, v0
	v_sub_u32_e32 v1, v3, v1
	v_ashrrev_i32_e32 v0, 6, v0
	v_lshrrev_b32_e32 v2, 4, v1
	v_bitop3_b32 v2, v2, v1, 32 bitop3:0x6c
	v_lshlrev_b32_e32 v1, 3, v0
	v_and_b32_e32 v4, -16, v1
	v_ashrrev_i32_e32 v1, 31, v2
	v_lshrrev_b32_e32 v1, 26, v1
	v_add_u32_e32 v5, v2, v1
	v_ashrrev_i32_e32 v1, 6, v5
	v_and_b32_e32 v5, 0xc0, v5
	v_sub_u32_e32 v2, v2, v5
	s_waitcnt lgkmcnt(0)
	v_mov_b32_e32 v9, 1
	v_lshlrev_b32_e32 v6, 5, v0
	v_ashrrev_i16_sdwa v2, v9, sext(v2) dst_sel:DWORD dst_unused:UNUSED_PAD src0_sel:DWORD src1_sel:BYTE_0
	v_and_b32_e32 v6, 32, v6
	v_bfe_i32 v2, v2, 0, 16
	v_add_u32_e32 v4, v1, v4
	v_and_b32_e32 v8, 3, v1
	s_mov_b32 s1, 0x1fffe0
	v_add_lshl_u32 v6, v6, v2, 1
	v_lshlrev_b32_e32 v5, 1, v4
	v_lshrrev_b32_e32 v7, 2, v4
	v_and_or_b32 v8, v4, s1, v8
	v_lshl_add_u32 v144, v4, 11, v6
	v_add_u32_e32 v4, 0x2000, v3
	v_ashrrev_i32_e32 v3, 31, v4
	v_lshrrev_b32_e32 v3, 22, v3
	v_and_b32_e32 v5, 24, v5
	v_and_b32_e32 v7, 4, v7
	v_add_u32_e32 v3, v4, v3
	v_or3_b32 v5, v8, v7, v5
	v_ashrrev_i32_e32 v3, 10, v3
	v_lshl_add_u32 v128, v5, 11, v6
	v_mul_i32_i24_e32 v5, 0x400, v3
	v_sub_u32_e32 v4, v4, v5
	v_lshrrev_b32_e32 v5, 4, v4
	v_bitop3_b32 v5, v5, v4, 32 bitop3:0x6c
	v_lshlrev_b32_e32 v4, 3, v3
	v_and_b32_e32 v6, -16, v4
	v_ashrrev_i32_e32 v4, 31, v5
	v_lshrrev_b32_e32 v4, 26, v4
	v_add_u32_e32 v7, v5, v4
	v_ashrrev_i32_e32 v4, 6, v7
	s_ashr_i32 s0, s48, 6
	v_add_u32_e32 v6, v4, v6
	v_and_b32_e32 v10, 3, v4
	s_ashr_i32 s15, s14, 31
	s_ashr_i32 s41, s40, 31
	v_and_b32_e32 v7, 0xc0, v7
	v_and_or_b32 v10, v6, s1, v10
	s_ashr_i32 s1, s48, 8
	s_lshl_b32 s92, s0, 10
	s_lshl_b64 s[8:9], s[14:15], 19
	s_lshl_b64 s[4:5], s[40:41], 19
	v_readlane_b32 s12, v252, 41
	v_sub_u32_e32 v5, v5, v7
	v_readlane_b32 s13, v252, 42
	s_add_u32 s18, s12, s4
	v_lshlrev_b32_e32 v8, 5, v3
	v_ashrrev_i16_sdwa v5, v9, sext(v5) dst_sel:DWORD dst_unused:UNUSED_PAD src0_sel:DWORD src1_sel:BYTE_0
	v_lshlrev_b32_e32 v7, 1, v6
	v_lshrrev_b32_e32 v9, 2, v6
	s_addc_u32 s19, s13, s5
	s_add_i32 s5, s92, 16
	v_and_b32_e32 v8, 32, v8
	v_bfe_i32 v5, v5, 0, 16
	v_and_b32_e32 v7, 24, v7
	v_and_b32_e32 v9, 4, v9
	s_add_i32 m0, s5, 0x10000
	v_or3_b32 v7, v10, v9, v7
	v_add_lshl_u32 v8, v8, v5, 1
	global_load_lds_dwordx4 v128, s[18:19]
	s_add_i32 m0, s5, 0x12000
	v_readlane_b32 s12, v252, 55
	v_lshl_add_u32 v148, v7, 11, v8
	v_readlane_b32 s13, v252, 56
	s_add_u32 s30, s12, s8
	global_load_lds_dwordx4 v148, s[18:19]
	s_addc_u32 s31, s13, s9
	s_mov_b32 m0, s5
	s_add_i32 s4, s5, 0x2000
	v_lshl_add_u32 v146, v6, 11, v8
	global_load_lds_dwordx4 v144, s[30:31]
	s_mov_b32 m0, s4
	s_add_u32 s8, s18, 0x40000
	global_load_lds_dwordx4 v146, s[30:31]
	s_addc_u32 s9, s19, 0
	s_add_i32 m0, s5, 0x14000
	s_nop 0
	global_load_lds_dwordx4 v128, s[8:9]
	s_add_i32 m0, s5, 0x16000
	s_nop 0
	global_load_lds_dwordx4 v148, s[8:9]
	s_add_u32 s8, s30, 0x40000
	s_addc_u32 s9, s31, 0
	s_add_i32 s36, s5, 0x4000
	s_mov_b32 m0, s36
	s_add_i32 s37, s5, 0x6000
	global_load_lds_dwordx4 v144, s[8:9]
	s_mov_b32 m0, s37
	s_cmp_lg_u32 s1, 1
	global_load_lds_dwordx4 v146, s[8:9]
.LBB0_266:
	v_lshrrev_b32_e32 v15, 1, v141
	v_and_b32_e32 v15, 24, v15
	v_lshl_add_u64 v[6:7], s[18:19], 0, v[128:129]
	v_mov_b32_e32 v149, v129
	v_and_b32_e32 v14, 15, v141
	v_lshlrev_b32_e32 v16, 1, v15
	s_lshl_b32 s0, s0, 5
	v_lshl_add_u64 v[8:9], s[18:19], 0, v[148:149]
	v_mov_b32_e32 v145, v129
	v_lshl_or_b32 v143, s1, 6, v14
	v_lshl_or_b32 v14, v14, 6, v16
	v_lshlrev_b32_e32 v16, 2, v141
	s_and_b32 s8, s0, 0x60
	s_add_i32 m0, s5, 0x18000
	v_lshl_add_u64 v[6:7], v[6:7], 0, s[28:29]
	v_lshl_add_u64 v[10:11], s[30:31], 0, v[144:145]
	v_mov_b32_e32 v147, v129
	s_lshl_b32 s1, s1, 13
	v_and_b32_e32 v16, 32, v16
	s_lshl_b32 s0, s8, 7
	s_waitcnt vmcnt(4)
	s_barrier
	global_load_lds_dwordx4 v[6:7], off
	v_lshl_add_u64 v[6:7], v[8:9], 0, s[28:29]
	s_add_i32 m0, s5, 0x1a000
	s_add_i32 s46, s5, 0x8000
	s_add_i32 s47, s5, 0xa000
	v_lshl_add_u64 v[12:13], s[30:31], 0, v[146:147]
	v_bitop3_b32 v162, s0, v14, v16 bitop3:0xf6
	global_load_lds_dwordx4 v[6:7], off
	v_lshl_add_u64 v[6:7], v[10:11], 0, s[28:29]
	s_mov_b32 m0, s46
	s_add_u32 s0, s18, 0x40080
	v_bitop3_b32 v17, v14, s1, v16 bitop3:0xde
	global_load_lds_dwordx4 v[6:7], off
	v_lshl_add_u64 v[6:7], v[12:13], 0, s[28:29]
	s_mov_b32 m0, s47
	s_addc_u32 s1, s19, 0
	global_load_lds_dwordx4 v[6:7], off
	s_add_i32 m0, s5, 0x1c000
	v_lshl_add_u64 v[6:7], s[0:1], 0, v[128:129]
	global_load_lds_dwordx4 v[6:7], off
	v_lshl_add_u64 v[6:7], s[0:1], 0, v[148:149]
	s_add_i32 m0, s5, 0x1e000
	v_or_b32_e32 v163, s8, v15
	global_load_lds_dwordx4 v[6:7], off
	v_lshlrev_b32_e32 v6, 14, v0
	v_and_b32_e32 v6, 0xffff8000, v6
	v_lshl_add_u32 v1, v1, 11, v6
	v_and_b32_e32 v0, 1, v0
	v_lshl_or_b32 v0, v0, 6, v1
	v_lshl_add_u32 v150, v2, 1, v0
	v_lshlrev_b32_e32 v0, 14, v3
	v_and_b32_e32 v0, 0xffff8000, v0
	s_waitcnt vmcnt(6)
	v_lshl_add_u32 v0, v4, 11, v0
	v_and_b32_e32 v1, 1, v3
	v_lshl_or_b32 v0, v1, 6, v0
	v_mov_b32_e32 v151, v129
	v_lshl_add_u32 v152, v5, 1, v0
	v_mov_b32_e32 v153, v129
	s_mov_b32 s16, 0
	v_add_u32_e32 v164, 16, v17
	s_barrier
	s_branch .LBB0_268

.LBB0_270:
	v_lshl_add_u32 v154, s14, 8, v143
	v_readlane_b32 s14, v252, 43
	v_mov_b64_e32 v[0:1], 0x600
	v_ashrrev_i32_e32 v155, 31, v154
	v_readlane_b32 s15, v252, 44
	v_cmp_lt_i64_e32 vcc, s[34:35], v[0:1]
	s_ashr_i32 s13, s12, 31
	v_lshl_add_u64 v[0:1], v[154:155], 2, s[14:15]
	global_load_dword v156, v[0:1], off
	global_load_dword v171, v[0:1], off offset:64
	global_load_dword v170, v[0:1], off offset:128
	global_load_dword v169, v[0:1], off offset:192
	global_load_dword v168, v[0:1], off offset:512
	global_load_dword v167, v[0:1], off offset:576
	global_load_dword v166, v[0:1], off offset:640
	global_load_dword v165, v[0:1], off offset:704
	s_lshl_b64 s[0:1], s[12:13], 19
	v_readlane_b32 s24, v252, 55
	v_readlane_b32 s25, v252, 56
	s_add_u32 s42, s24, s0
	s_addc_u32 s43, s25, s1
	s_and_b64 s[0:1], vcc, exec
	s_cselect_b32 s0, s43, s31
	s_cselect_b32 s1, s42, s30
	s_ashr_i32 s9, s8, 31
	s_lshl_b64 s[24:25], s[8:9], 19
	v_readlane_b32 s34, v252, 41
	v_readlane_b32 s35, v252, 42
	s_add_u32 s44, s34, s24
	s_addc_u32 s45, s35, s25
	s_and_b64 s[24:25], vcc, exec
	s_cselect_b32 s9, s45, s19
	s_cselect_b32 s13, s44, s18
	s_add_u32 s30, s30, 0x40080
	s_addc_u32 s31, s31, 0
	s_add_u32 s17, s18, 0x100
	v_mov_b32_e32 v0, 0
	s_addc_u32 s24, s19, 0
	s_mov_b32 s25, -2
	v_mov_b32_e32 v1, v0
	v_mov_b32_e32 v2, v0
	v_mov_b32_e32 v3, v0
	v_mov_b32_e32 v4, v0
	v_mov_b32_e32 v5, v0
	v_mov_b32_e32 v6, v0
	v_mov_b32_e32 v7, v0
	v_mov_b32_e32 v16, v0
	v_mov_b32_e32 v17, v0
	v_mov_b32_e32 v18, v0
	v_mov_b32_e32 v19, v0
	v_mov_b32_e32 v20, v0
	v_mov_b32_e32 v21, v0
	v_mov_b32_e32 v22, v0
	v_mov_b32_e32 v23, v0
	v_mov_b32_e32 v32, v0
	v_mov_b32_e32 v33, v0
	v_mov_b32_e32 v34, v0
	v_mov_b32_e32 v35, v0
	v_mov_b32_e32 v36, v0
	v_mov_b32_e32 v37, v0
	v_mov_b32_e32 v38, v0
	v_mov_b32_e32 v39, v0
	v_mov_b32_e32 v48, v0
	v_mov_b32_e32 v49, v0
	v_mov_b32_e32 v50, v0
	v_mov_b32_e32 v51, v0
	v_mov_b32_e32 v52, v0
	v_mov_b32_e32 v53, v0
	v_mov_b32_e32 v54, v0
	v_mov_b32_e32 v55, v0
	v_mov_b32_e32 v8, v0
	v_mov_b32_e32 v9, v0
	v_mov_b32_e32 v10, v0
	v_mov_b32_e32 v11, v0
	v_mov_b32_e32 v12, v0
	v_mov_b32_e32 v13, v0
	v_mov_b32_e32 v14, v0
	v_mov_b32_e32 v15, v0
	v_mov_b32_e32 v24, v0
	v_mov_b32_e32 v25, v0
	v_mov_b32_e32 v26, v0
	v_mov_b32_e32 v27, v0
	v_mov_b32_e32 v28, v0
	v_mov_b32_e32 v29, v0
	v_mov_b32_e32 v30, v0
	v_mov_b32_e32 v31, v0
	v_mov_b32_e32 v40, v0
	v_mov_b32_e32 v41, v0
	v_mov_b32_e32 v42, v0
	v_mov_b32_e32 v43, v0
	v_mov_b32_e32 v44, v0
	v_mov_b32_e32 v45, v0
	v_mov_b32_e32 v46, v0
	v_mov_b32_e32 v47, v0
	v_mov_b32_e32 v56, v0
	v_mov_b32_e32 v57, v0
	v_mov_b32_e32 v58, v0
	v_mov_b32_e32 v59, v0
	v_mov_b32_e32 v60, v0
	v_mov_b32_e32 v61, v0
	v_mov_b32_e32 v62, v0
	v_mov_b32_e32 v63, v0
	v_mov_b32_e32 v64, v0
	v_mov_b32_e32 v65, v0
	v_mov_b32_e32 v66, v0
	v_mov_b32_e32 v67, v0
	v_mov_b32_e32 v68, v0
	v_mov_b32_e32 v69, v0
	v_mov_b32_e32 v70, v0
	v_mov_b32_e32 v71, v0
	v_mov_b32_e32 v80, v0
	v_mov_b32_e32 v81, v0
	v_mov_b32_e32 v82, v0
	v_mov_b32_e32 v83, v0
	v_mov_b32_e32 v84, v0
	v_mov_b32_e32 v85, v0
	v_mov_b32_e32 v86, v0
	v_mov_b32_e32 v87, v0
	v_mov_b32_e32 v96, v0
	v_mov_b32_e32 v97, v0
	v_mov_b32_e32 v98, v0
	v_mov_b32_e32 v99, v0
	v_mov_b32_e32 v100, v0
	v_mov_b32_e32 v101, v0
	v_mov_b32_e32 v102, v0
	v_mov_b32_e32 v103, v0
	v_mov_b32_e32 v112, v0
	v_mov_b32_e32 v113, v0
	v_mov_b32_e32 v114, v0
	v_mov_b32_e32 v115, v0
	v_mov_b32_e32 v116, v0
	v_mov_b32_e32 v117, v0
	v_mov_b32_e32 v118, v0
	v_mov_b32_e32 v119, v0
	v_mov_b32_e32 v72, v0
	v_mov_b32_e32 v73, v0
	v_mov_b32_e32 v74, v0
	v_mov_b32_e32 v75, v0
	v_mov_b32_e32 v76, v0
	v_mov_b32_e32 v77, v0
	v_mov_b32_e32 v78, v0
	v_mov_b32_e32 v79, v0
	v_mov_b32_e32 v88, v0
	v_mov_b32_e32 v89, v0
	v_mov_b32_e32 v90, v0
	v_mov_b32_e32 v91, v0
	v_mov_b32_e32 v92, v0
	v_mov_b32_e32 v93, v0
	v_mov_b32_e32 v94, v0
	v_mov_b32_e32 v95, v0
	v_mov_b32_e32 v104, v0
	v_mov_b32_e32 v105, v0
	v_mov_b32_e32 v106, v0
	v_mov_b32_e32 v107, v0
	v_mov_b32_e32 v108, v0
	v_mov_b32_e32 v109, v0
	v_mov_b32_e32 v110, v0
	v_mov_b32_e32 v111, v0
	v_mov_b32_e32 v120, v0
	v_mov_b32_e32 v121, v0
	v_mov_b32_e32 v122, v0
	v_mov_b32_e32 v123, v0
	v_mov_b32_e32 v124, v0
	v_mov_b32_e32 v125, v0
	v_mov_b32_e32 v126, v0
	v_mov_b32_e32 v127, v0
	s_cmpk_gt_u32 s48, 0xff
	s_cbranch_scc0 .Lgin_enter
	s_barrier
.Lgin_enter:
.LBB0_271:
	s_add_u32 s14, s30, 0xfffc0080
	s_addc_u32 s15, s31, -1
	s_add_i32 s20, 16, 0x10000
	v_add_u32_e32 v130, s20, v162
	ds_read_b128 v[158:161], v130
	ds_read_b128 v[172:175], v130 offset:1024
	ds_read_b128 v[176:179], v130 offset:2048
	ds_read_b128 v[180:183], v130 offset:3072
	s_cmp_eq_u32 s25, 12
	s_cselect_b32 s19, s0, s15
	s_cselect_b32 s18, s1, s14
	s_cselect_b32 s15, s9, s24
	s_cselect_b32 s14, s13, s17
	v_lshl_add_u64 v[130:131], s[30:31], 0, v[150:151]
	s_add_i32 m0, s5, 0xc000
	ds_read_b128 v[184:187], v164
	ds_read_b128 v[188:191], v164 offset:1024
	ds_read_b128 v[192:195], v164 offset:2048
	ds_read_b128 v[196:199], v164 offset:3072
	ds_read_b128 v[200:203], v164 offset:4096
	ds_read_b128 v[204:207], v164 offset:5120
	ds_read_b128 v[208:211], v164 offset:6144
	ds_read_b128 v[212:215], v164 offset:7168
	global_load_lds_dwordx4 v[130:131], off
	v_lshl_add_u64 v[130:131], s[30:31], 0, v[152:153]
	s_add_i32 m0, s5, 0xe000
	s_nop 0
	global_load_lds_dwordx4 v[130:131], off
	s_add_i32 s41, 16, 0x14000
	v_add_u32_e32 v130, s41, v162
	ds_read_b128 v[216:219], v130
	ds_read_b128 v[220:223], v130 offset:1024
	ds_read_b128 v[224:227], v130 offset:2048
	ds_read_b128 v[228:231], v130 offset:3072
	s_waitcnt vmcnt(8) lgkmcnt(0)
	s_barrier
	s_setprio 1
	v_mfma_f32_16x16x32_bf16 v[124:127], v[158:161], v[184:187], v[124:127]
	v_mfma_f32_16x16x32_bf16 v[120:123], v[176:179], v[184:187], v[120:123]
	v_mfma_f32_16x16x32_bf16 v[108:111], v[158:161], v[192:195], v[108:111]
	v_mfma_f32_16x16x32_bf16 v[104:107], v[176:179], v[192:195], v[104:107]
	v_mfma_f32_16x16x32_bf16 v[92:95], v[158:161], v[200:203], v[92:95]
	v_mfma_f32_16x16x32_bf16 v[88:91], v[176:179], v[200:203], v[88:91]
	v_mfma_f32_16x16x32_bf16 v[76:79], v[158:161], v[208:211], v[76:79]
	v_mfma_f32_16x16x32_bf16 v[72:75], v[176:179], v[208:211], v[72:75]
	v_mfma_f32_16x16x32_bf16 v[124:127], v[172:175], v[188:191], v[124:127]
	v_mfma_f32_16x16x32_bf16 v[120:123], v[180:183], v[188:191], v[120:123]
	v_mfma_f32_16x16x32_bf16 v[108:111], v[172:175], v[196:199], v[108:111]
	v_mfma_f32_16x16x32_bf16 v[104:107], v[180:183], v[196:199], v[104:107]
	v_mfma_f32_16x16x32_bf16 v[92:95], v[172:175], v[204:207], v[92:95]
	v_mfma_f32_16x16x32_bf16 v[88:91], v[180:183], v[204:207], v[88:91]
	v_mfma_f32_16x16x32_bf16 v[76:79], v[172:175], v[212:215], v[76:79]
	v_mfma_f32_16x16x32_bf16 v[72:75], v[180:183], v[212:215], v[72:75]
	v_mfma_f32_16x16x32_bf16 v[116:119], v[216:219], v[184:187], v[116:119]
	v_mfma_f32_16x16x32_bf16 v[112:115], v[224:227], v[184:187], v[112:115]
	v_mfma_f32_16x16x32_bf16 v[100:103], v[216:219], v[192:195], v[100:103]
	v_mfma_f32_16x16x32_bf16 v[96:99], v[224:227], v[192:195], v[96:99]
	v_mfma_f32_16x16x32_bf16 v[84:87], v[216:219], v[200:203], v[84:87]
	v_mfma_f32_16x16x32_bf16 v[80:83], v[224:227], v[200:203], v[80:83]
	v_mfma_f32_16x16x32_bf16 v[68:71], v[216:219], v[208:211], v[68:71]
	v_mfma_f32_16x16x32_bf16 v[64:67], v[224:227], v[208:211], v[64:67]
	v_mfma_f32_16x16x32_bf16 v[116:119], v[220:223], v[188:191], v[116:119]
	v_mfma_f32_16x16x32_bf16 v[112:115], v[228:231], v[188:191], v[112:115]
	v_mfma_f32_16x16x32_bf16 v[100:103], v[220:223], v[196:199], v[100:103]
	v_mfma_f32_16x16x32_bf16 v[96:99], v[228:231], v[196:199], v[96:99]
	v_mfma_f32_16x16x32_bf16 v[84:87], v[220:223], v[204:207], v[84:87]
	v_mfma_f32_16x16x32_bf16 v[80:83], v[228:231], v[204:207], v[80:83]
	v_mfma_f32_16x16x32_bf16 v[68:71], v[220:223], v[212:215], v[68:71]
	v_mfma_f32_16x16x32_bf16 v[64:67], v[228:231], v[212:215], v[64:67]
	s_setprio 0
	s_barrier
	ds_read_b128 v[184:187], v164 offset:16384
	ds_read_b128 v[188:191], v164 offset:17408
	ds_read_b128 v[192:195], v164 offset:18432
	ds_read_b128 v[196:199], v164 offset:19456
	ds_read_b128 v[200:203], v164 offset:20480
	ds_read_b128 v[204:207], v164 offset:21504
	ds_read_b128 v[208:211], v164 offset:22528
	ds_read_b128 v[212:215], v164 offset:23552
	s_add_i32 s20, s20, s92
	v_lshl_add_u64 v[130:131], s[14:15], 0, v[128:129]
	s_mov_b32 m0, s20
	v_lshl_add_u64 v[132:133], s[14:15], 0, v[148:149]
	global_load_lds_dwordx4 v[130:131], off
	s_add_i32 m0, s20, 0x2000
	s_nop 0
	global_load_lds_dwordx4 v[132:133], off
	s_mov_b32 m0, s5
	v_lshl_add_u64 v[134:135], s[18:19], 0, v[144:145]
	global_load_lds_dwordx4 v[134:135], off
	v_lshl_add_u64 v[136:137], s[18:19], 0, v[146:147]
	s_mov_b32 m0, s4
	s_nop 0
	global_load_lds_dwordx4 v[136:137], off
	s_add_u32 s34, s14, 0x40000
	s_addc_u32 s35, s15, 0
	s_add_i32 s20, s41, s92
	v_lshl_add_u64 v[138:139], s[34:35], 0, v[128:129]
	s_mov_b32 m0, s20
	s_nop 0
	global_load_lds_dwordx4 v[138:139], off
	v_lshl_add_u64 v[138:139], s[34:35], 0, v[148:149]
	s_add_i32 m0, s20, 0x2000
	s_nop 0
	global_load_lds_dwordx4 v[138:139], off
	s_waitcnt vmcnt(8) lgkmcnt(0)
	s_barrier
	s_setprio 1
	v_mfma_f32_16x16x32_bf16 v[60:63], v[158:161], v[184:187], v[60:63]
	v_mfma_f32_16x16x32_bf16 v[56:59], v[176:179], v[184:187], v[56:59]
	v_mfma_f32_16x16x32_bf16 v[44:47], v[158:161], v[192:195], v[44:47]
	v_mfma_f32_16x16x32_bf16 v[40:43], v[176:179], v[192:195], v[40:43]
	v_mfma_f32_16x16x32_bf16 v[28:31], v[158:161], v[200:203], v[28:31]
	v_mfma_f32_16x16x32_bf16 v[24:27], v[176:179], v[200:203], v[24:27]
	v_mfma_f32_16x16x32_bf16 v[12:15], v[158:161], v[208:211], v[12:15]
	v_mfma_f32_16x16x32_bf16 v[8:11], v[176:179], v[208:211], v[8:11]
	v_mfma_f32_16x16x32_bf16 v[60:63], v[172:175], v[188:191], v[60:63]
	v_mfma_f32_16x16x32_bf16 v[56:59], v[180:183], v[188:191], v[56:59]
	v_mfma_f32_16x16x32_bf16 v[44:47], v[172:175], v[196:199], v[44:47]
	v_mfma_f32_16x16x32_bf16 v[40:43], v[180:183], v[196:199], v[40:43]
	v_mfma_f32_16x16x32_bf16 v[28:31], v[172:175], v[204:207], v[28:31]
	v_mfma_f32_16x16x32_bf16 v[24:27], v[180:183], v[204:207], v[24:27]
	v_mfma_f32_16x16x32_bf16 v[12:15], v[172:175], v[212:215], v[12:15]
	v_mfma_f32_16x16x32_bf16 v[8:11], v[180:183], v[212:215], v[8:11]
	v_mfma_f32_16x16x32_bf16 v[52:55], v[216:219], v[184:187], v[52:55]
	v_mfma_f32_16x16x32_bf16 v[48:51], v[224:227], v[184:187], v[48:51]
	v_mfma_f32_16x16x32_bf16 v[36:39], v[216:219], v[192:195], v[36:39]
	v_mfma_f32_16x16x32_bf16 v[32:35], v[224:227], v[192:195], v[32:35]
	v_mfma_f32_16x16x32_bf16 v[20:23], v[216:219], v[200:203], v[20:23]
	v_mfma_f32_16x16x32_bf16 v[16:19], v[224:227], v[200:203], v[16:19]
	v_mfma_f32_16x16x32_bf16 v[4:7], v[216:219], v[208:211], v[4:7]
	v_mfma_f32_16x16x32_bf16 v[0:3], v[224:227], v[208:211], v[0:3]
	v_mfma_f32_16x16x32_bf16 v[52:55], v[220:223], v[188:191], v[52:55]
	v_mfma_f32_16x16x32_bf16 v[48:51], v[228:231], v[188:191], v[48:51]
	v_mfma_f32_16x16x32_bf16 v[36:39], v[220:223], v[196:199], v[36:39]
	v_mfma_f32_16x16x32_bf16 v[32:35], v[228:231], v[196:199], v[32:35]
	v_mfma_f32_16x16x32_bf16 v[20:23], v[220:223], v[204:207], v[20:23]
	v_mfma_f32_16x16x32_bf16 v[16:19], v[228:231], v[204:207], v[16:19]
	v_mfma_f32_16x16x32_bf16 v[4:7], v[220:223], v[212:215], v[4:7]
	v_mfma_f32_16x16x32_bf16 v[0:3], v[228:231], v[212:215], v[0:3]
	s_setprio 0
	s_add_i32 s20, 16, 0x18000
	v_add_u32_e32 v138, s20, v162
	s_barrier
	ds_read_b128 v[158:161], v138
	ds_read_b128 v[172:175], v138 offset:1024
	ds_read_b128 v[176:179], v138 offset:2048
	ds_read_b128 v[180:183], v138 offset:3072
	s_add_u32 s18, s18, 0x40000
	s_addc_u32 s19, s19, 0
	s_mov_b32 m0, s36
	v_lshl_add_u64 v[216:217], s[18:19], 0, v[144:145]
	ds_read_b128 v[184:187], v164 offset:32768
	ds_read_b128 v[188:191], v164 offset:33792
	ds_read_b128 v[192:195], v164 offset:34816
	ds_read_b128 v[196:199], v164 offset:35840
	ds_read_b128 v[200:203], v164 offset:36864
	ds_read_b128 v[204:207], v164 offset:37888
	ds_read_b128 v[208:211], v164 offset:38912
	ds_read_b128 v[212:215], v164 offset:39936
	global_load_lds_dwordx4 v[216:217], off
	v_lshl_add_u64 v[216:217], s[18:19], 0, v[146:147]
	s_mov_b32 m0, s37
	s_nop 0
	global_load_lds_dwordx4 v[216:217], off
	s_add_i32 s18, 16, 0x1c000
	v_add_u32_e32 v138, s18, v162
	ds_read_b128 v[216:219], v138
	ds_read_b128 v[220:223], v138 offset:1024
	ds_read_b128 v[224:227], v138 offset:2048
	ds_read_b128 v[228:231], v138 offset:3072
	s_waitcnt vmcnt(8) lgkmcnt(0)
	s_barrier
	s_setprio 1
	v_mfma_f32_16x16x32_bf16 v[124:127], v[158:161], v[184:187], v[124:127]
	v_mfma_f32_16x16x32_bf16 v[120:123], v[176:179], v[184:187], v[120:123]
	v_mfma_f32_16x16x32_bf16 v[108:111], v[158:161], v[192:195], v[108:111]
	v_mfma_f32_16x16x32_bf16 v[104:107], v[176:179], v[192:195], v[104:107]
	v_mfma_f32_16x16x32_bf16 v[92:95], v[158:161], v[200:203], v[92:95]
	v_mfma_f32_16x16x32_bf16 v[88:91], v[176:179], v[200:203], v[88:91]
	v_mfma_f32_16x16x32_bf16 v[76:79], v[158:161], v[208:211], v[76:79]
	v_mfma_f32_16x16x32_bf16 v[72:75], v[176:179], v[208:211], v[72:75]
	v_mfma_f32_16x16x32_bf16 v[124:127], v[172:175], v[188:191], v[124:127]
	v_mfma_f32_16x16x32_bf16 v[120:123], v[180:183], v[188:191], v[120:123]
	v_mfma_f32_16x16x32_bf16 v[108:111], v[172:175], v[196:199], v[108:111]
	v_mfma_f32_16x16x32_bf16 v[104:107], v[180:183], v[196:199], v[104:107]
	v_mfma_f32_16x16x32_bf16 v[92:95], v[172:175], v[204:207], v[92:95]
	v_mfma_f32_16x16x32_bf16 v[88:91], v[180:183], v[204:207], v[88:91]
	v_mfma_f32_16x16x32_bf16 v[76:79], v[172:175], v[212:215], v[76:79]
	v_mfma_f32_16x16x32_bf16 v[72:75], v[180:183], v[212:215], v[72:75]
	v_mfma_f32_16x16x32_bf16 v[116:119], v[216:219], v[184:187], v[116:119]
	v_mfma_f32_16x16x32_bf16 v[112:115], v[224:227], v[184:187], v[112:115]
	v_mfma_f32_16x16x32_bf16 v[100:103], v[216:219], v[192:195], v[100:103]
	v_mfma_f32_16x16x32_bf16 v[96:99], v[224:227], v[192:195], v[96:99]
	v_mfma_f32_16x16x32_bf16 v[84:87], v[216:219], v[200:203], v[84:87]
	v_mfma_f32_16x16x32_bf16 v[80:83], v[224:227], v[200:203], v[80:83]
	v_mfma_f32_16x16x32_bf16 v[68:71], v[216:219], v[208:211], v[68:71]
	v_mfma_f32_16x16x32_bf16 v[64:67], v[224:227], v[208:211], v[64:67]
	v_mfma_f32_16x16x32_bf16 v[116:119], v[220:223], v[188:191], v[116:119]
	v_mfma_f32_16x16x32_bf16 v[112:115], v[228:231], v[188:191], v[112:115]
	v_mfma_f32_16x16x32_bf16 v[100:103], v[220:223], v[196:199], v[100:103]
	v_mfma_f32_16x16x32_bf16 v[96:99], v[228:231], v[196:199], v[96:99]
	v_mfma_f32_16x16x32_bf16 v[84:87], v[220:223], v[204:207], v[84:87]
	v_mfma_f32_16x16x32_bf16 v[80:83], v[228:231], v[204:207], v[80:83]
	v_mfma_f32_16x16x32_bf16 v[68:71], v[220:223], v[212:215], v[68:71]
	v_mfma_f32_16x16x32_bf16 v[64:67], v[228:231], v[212:215], v[64:67]
	s_setprio 0
	s_barrier
	ds_read_b128 v[184:187], v164 offset:49152
	ds_read_b128 v[188:191], v164 offset:50176
	ds_read_b128 v[192:195], v164 offset:51200
	ds_read_b128 v[196:199], v164 offset:52224
	ds_read_b128 v[200:203], v164 offset:53248
	ds_read_b128 v[204:207], v164 offset:54272
	ds_read_b128 v[208:211], v164 offset:55296
	ds_read_b128 v[212:215], v164 offset:56320
	s_add_i32 s19, s20, s92
	v_lshl_add_u64 v[130:131], v[130:131], 0, s[28:29]
	s_mov_b32 m0, s19
	s_nop 0
	global_load_lds_dwordx4 v[130:131], off
	v_lshl_add_u64 v[130:131], v[132:133], 0, s[28:29]
	s_add_i32 m0, s19, 0x2000
	s_nop 0
	global_load_lds_dwordx4 v[130:131], off
	s_mov_b32 m0, s46
	v_lshl_add_u64 v[130:131], v[134:135], 0, s[28:29]
	global_load_lds_dwordx4 v[130:131], off
	v_lshl_add_u64 v[130:131], v[136:137], 0, s[28:29]
	s_mov_b32 m0, s47
	s_nop 0
	global_load_lds_dwordx4 v[130:131], off
	s_add_u32 s14, s14, 0x40080
	s_addc_u32 s15, s15, 0
	s_add_i32 s18, s18, s92
	v_lshl_add_u64 v[130:131], s[14:15], 0, v[128:129]
	s_mov_b32 m0, s18
	s_nop 0
	global_load_lds_dwordx4 v[130:131], off
	v_lshl_add_u64 v[130:131], s[14:15], 0, v[148:149]
	s_add_i32 m0, s18, 0x2000
	s_nop 0
	global_load_lds_dwordx4 v[130:131], off
	s_waitcnt vmcnt(8) lgkmcnt(0)
	s_barrier
	s_setprio 1
	v_mfma_f32_16x16x32_bf16 v[60:63], v[158:161], v[184:187], v[60:63]
	v_mfma_f32_16x16x32_bf16 v[56:59], v[176:179], v[184:187], v[56:59]
	v_mfma_f32_16x16x32_bf16 v[44:47], v[158:161], v[192:195], v[44:47]
	v_mfma_f32_16x16x32_bf16 v[40:43], v[176:179], v[192:195], v[40:43]
	v_mfma_f32_16x16x32_bf16 v[28:31], v[158:161], v[200:203], v[28:31]
	v_mfma_f32_16x16x32_bf16 v[24:27], v[176:179], v[200:203], v[24:27]
	v_mfma_f32_16x16x32_bf16 v[12:15], v[158:161], v[208:211], v[12:15]
	v_mfma_f32_16x16x32_bf16 v[8:11], v[176:179], v[208:211], v[8:11]
	v_mfma_f32_16x16x32_bf16 v[60:63], v[172:175], v[188:191], v[60:63]
	v_mfma_f32_16x16x32_bf16 v[56:59], v[180:183], v[188:191], v[56:59]
	v_mfma_f32_16x16x32_bf16 v[44:47], v[172:175], v[196:199], v[44:47]
	v_mfma_f32_16x16x32_bf16 v[40:43], v[180:183], v[196:199], v[40:43]
	v_mfma_f32_16x16x32_bf16 v[28:31], v[172:175], v[204:207], v[28:31]
	v_mfma_f32_16x16x32_bf16 v[24:27], v[180:183], v[204:207], v[24:27]
	v_mfma_f32_16x16x32_bf16 v[12:15], v[172:175], v[212:215], v[12:15]
	v_mfma_f32_16x16x32_bf16 v[8:11], v[180:183], v[212:215], v[8:11]
	v_mfma_f32_16x16x32_bf16 v[52:55], v[216:219], v[184:187], v[52:55]
	v_mfma_f32_16x16x32_bf16 v[48:51], v[224:227], v[184:187], v[48:51]
	v_mfma_f32_16x16x32_bf16 v[36:39], v[216:219], v[192:195], v[36:39]
	v_mfma_f32_16x16x32_bf16 v[32:35], v[224:227], v[192:195], v[32:35]
	v_mfma_f32_16x16x32_bf16 v[20:23], v[216:219], v[200:203], v[20:23]
	v_mfma_f32_16x16x32_bf16 v[16:19], v[224:227], v[200:203], v[16:19]
	v_mfma_f32_16x16x32_bf16 v[4:7], v[216:219], v[208:211], v[4:7]
	v_mfma_f32_16x16x32_bf16 v[0:3], v[224:227], v[208:211], v[0:3]
	v_mfma_f32_16x16x32_bf16 v[52:55], v[220:223], v[188:191], v[52:55]
	v_mfma_f32_16x16x32_bf16 v[48:51], v[228:231], v[188:191], v[48:51]
	v_mfma_f32_16x16x32_bf16 v[36:39], v[220:223], v[196:199], v[36:39]
	v_mfma_f32_16x16x32_bf16 v[32:35], v[228:231], v[196:199], v[32:35]
	v_mfma_f32_16x16x32_bf16 v[20:23], v[220:223], v[204:207], v[20:23]
	v_mfma_f32_16x16x32_bf16 v[16:19], v[228:231], v[204:207], v[16:19]
	v_mfma_f32_16x16x32_bf16 v[4:7], v[220:223], v[212:215], v[4:7]
	v_mfma_f32_16x16x32_bf16 v[0:3], v[228:231], v[212:215], v[0:3]
	s_setprio 0
	s_add_i32 s25, s25, 2
	s_add_u32 s30, s30, 0x100
	s_addc_u32 s31, s31, 0
	s_add_u32 s17, s17, 0x100
	s_addc_u32 s24, s24, 0
	s_cmp_gt_u32 s25, 13
	s_cbranch_scc1 .Lgin_exit
	s_barrier
	s_branch .LBB0_271
.Lgin_exit:
	s_cmpk_gt_u32 s48, 0xff
	s_cbranch_scc1 .Lgin_epi
	s_barrier
.Lgin_epi:
	s_waitcnt vmcnt(0)
	v_fmamk_f32 v130, v156, 0x3a800000, v235
	v_mul_f32_e32 v131, 0x4b800000, v130
	v_cmp_gt_f32_e32 vcc, s86, v130
	s_cmp_lt_i32 s40, 4
	s_cselect_b64 s[14:15], -1, 0
	v_cndmask_b32_e32 v130, v130, v131, vcc
	v_rsq_f32_e32 v130, v130
	s_cmp_gt_i32 s40, 3
	v_mul_f32_e32 v131, 0x45800000, v130
	v_cndmask_b32_e32 v156, v130, v131, vcc
	v_pk_mul_f32 v[126:127], v[156:157], v[126:127] op_sel_hi:[0,1]
	v_pk_mul_f32 v[124:125], v[156:157], v[124:125] op_sel_hi:[0,1]
	v_pk_mul_f32 v[158:159], v[156:157], v[122:123] op_sel_hi:[0,1]
	v_pk_mul_f32 v[160:161], v[156:157], v[120:121] op_sel_hi:[0,1]
	s_cbranch_scc1 .LBB0_274
	v_mul_f32_e32 v121, 0x3d372713, v160
	v_mul_f32_e32 v121, v160, v121
	v_fma_f32 v121, v160, v121, v160
	v_mul_f32_e32 v121, 0x3fcc422a, v121
	v_mul_f32_e32 v121, 0xbfb8aa3b, v121
	v_exp_f32_e32 v121, v121
	v_mul_f32_e32 v120, 0x3d372713, v124
	v_mul_f32_e32 v120, v124, v120
	v_mov_b32_e32 v123, v125
	v_add_f32_e32 v121, 1.0, v121
	v_rcp_f32_e32 v122, v121
	v_mul_f32_e32 v121, 0x3d372713, v125
	v_mul_f32_e32 v121, v125, v121
	v_fma_f32 v120, v124, v120, v124
	v_fmac_f32_e32 v123, v123, v121
	v_mul_f32_e32 v120, 0x3fcc422a, v120
	v_mul_f32_e32 v121, 0x3fcc422a, v123
	v_mul_f32_e32 v120, 0xbfb8aa3b, v120
	v_mul_f32_e32 v121, 0xbfb8aa3b, v121
	v_mul_f32_e32 v131, 0x3d372713, v158
	v_exp_f32_e32 v120, v120
	v_exp_f32_e32 v121, v121
	v_mul_f32_e32 v131, v158, v131
	v_fma_f32 v131, v158, v131, v158
	v_mul_f32_e32 v131, 0x3fcc422a, v131
	v_mul_f32_e32 v131, 0xbfb8aa3b, v131
	v_add_f32_e32 v120, 1.0, v120
	v_add_f32_e32 v121, 1.0, v121
	v_exp_f32_e32 v131, v131
	v_rcp_f32_e32 v120, v120
	v_rcp_f32_e32 v121, v121
	v_mul_f32_e32 v123, 0x3d372713, v161
	v_mul_f32_e32 v123, v161, v123
	v_mov_b32_e32 v130, v161
	v_fmac_f32_e32 v130, v130, v123
	v_add_f32_e32 v131, 1.0, v131
	v_mul_f32_e32 v123, 0x3fcc422a, v130
	v_mul_f32_e32 v130, 0x3d372713, v126
	v_rcp_f32_e32 v132, v131
	v_mul_f32_e32 v131, 0x3d372713, v127
	v_pk_mul_f32 v[124:125], v[124:125], v[120:121]
	v_mul_f32_e32 v120, 0x3d372713, v159
	v_mul_f32_e32 v130, v126, v130
	v_mul_f32_e32 v131, v127, v131
	v_mul_f32_e32 v120, v159, v120
	v_fma_f32 v130, v126, v130, v126
	v_fma_f32 v131, v127, v131, v127
	v_fma_f32 v120, v159, v120, v159
	v_mul_f32_e32 v130, 0x3fcc422a, v130
	v_mul_f32_e32 v131, 0x3fcc422a, v131
	v_mul_f32_e32 v120, 0x3fcc422a, v120
	v_mul_f32_e32 v123, 0xbfb8aa3b, v123
	v_mul_f32_e32 v130, 0xbfb8aa3b, v130
	v_mul_f32_e32 v131, 0xbfb8aa3b, v131
	v_mul_f32_e32 v120, 0xbfb8aa3b, v120
	v_exp_f32_e32 v123, v123
	v_exp_f32_e32 v130, v130
	v_exp_f32_e32 v131, v131
	v_exp_f32_e32 v120, v120
	v_add_f32_e32 v123, 1.0, v123
	v_add_f32_e32 v130, 1.0, v130
	v_add_f32_e32 v131, 1.0, v131
	v_add_f32_e32 v120, 1.0, v120
	v_rcp_f32_e32 v123, v123
	v_rcp_f32_e32 v130, v130
	v_rcp_f32_e32 v131, v131
	v_rcp_f32_e32 v133, v120
	v_pk_mul_f32 v[160:161], v[160:161], v[122:123]
	v_pk_mul_f32 v[126:127], v[126:127], v[130:131]
	v_pk_mul_f32 v[158:159], v[158:159], v[132:133]

.LBB0_304:
	s_waitcnt vmcnt(0)
	s_movk_i32 s16, 0x300

.LBB0_333:
	s_and_b64 vcc, exec, s[38:39]
	s_cbranch_vccnz .LBB0_381
	v_bfe_i32 v1, v141, 27, 1
	v_lshlrev_b32_e32 v3, 4, v141
	v_lshrrev_b32_e32 v1, 22, v1
	v_ashrrev_i32_e32 v0, 31, v141
	v_add_u32_e32 v1, v3, v1
	v_lshrrev_b32_e32 v0, 26, v0
	v_and_b32_e32 v1, 0xfffffc00, v1
	v_add_u32_e32 v0, v141, v0
	v_sub_u32_e32 v1, v3, v1
	v_ashrrev_i32_e32 v0, 6, v0
	v_lshrrev_b32_e32 v2, 4, v1
	v_bitop3_b32 v2, v2, v1, 32 bitop3:0x6c
	v_lshlrev_b32_e32 v1, 3, v0
	v_and_b32_e32 v4, -16, v1
	v_ashrrev_i32_e32 v1, 31, v2
	v_lshrrev_b32_e32 v1, 26, v1
	v_add_u32_e32 v5, v2, v1
	v_ashrrev_i32_e32 v1, 6, v5
	v_and_b32_e32 v5, 0xc0, v5
	v_add_u32_e32 v6, v1, v4
	v_sub_u32_e32 v2, v2, v5
	s_waitcnt lgkmcnt(0)
	v_mov_b32_e32 v9, 1
	v_lshlrev_b32_e32 v4, 5, v0
	v_ashrrev_i16_sdwa v2, v9, sext(v2) dst_sel:DWORD dst_unused:UNUSED_PAD src0_sel:DWORD src1_sel:BYTE_0
	v_lshlrev_b32_e32 v5, 1, v6
	v_lshrrev_b32_e32 v7, 2, v6
	v_and_b32_e32 v8, 3, v1
	s_mov_b32 s1, 0x7fffe0
	v_and_b32_e32 v4, 32, v4
	v_bfe_i32 v2, v2, 0, 16
	v_and_b32_e32 v5, 24, v5
	v_and_b32_e32 v7, 4, v7
	v_and_or_b32 v8, v6, s1, v8
	v_or3_b32 v5, v8, v7, v5
	v_add_lshl_u32 v4, v4, v2, 1
	s_movk_i32 s8, 0x1600
	v_mad_u64_u32 v[144:145], s[4:5], v6, s8, v[4:5]
	v_mad_u32_u24 v128, v5, s8, v4
	v_add_u32_e32 v4, 0x2000, v3
	v_ashrrev_i32_e32 v3, 31, v4
	v_lshrrev_b32_e32 v3, 22, v3
	v_add_u32_e32 v3, v4, v3
	v_ashrrev_i32_e32 v3, 10, v3
	v_mul_i32_i24_e32 v5, 0x400, v3
	v_sub_u32_e32 v4, v4, v5
	v_lshrrev_b32_e32 v5, 4, v4
	v_bitop3_b32 v5, v5, v4, 32 bitop3:0x6c
	v_lshlrev_b32_e32 v4, 3, v3
	v_and_b32_e32 v6, -16, v4
	v_ashrrev_i32_e32 v4, 31, v5
	v_lshrrev_b32_e32 v4, 26, v4
	v_add_u32_e32 v7, v5, v4
	v_ashrrev_i32_e32 v4, 6, v7
	v_and_b32_e32 v7, 0xc0, v7
	v_add_u32_e32 v8, v4, v6
	v_sub_u32_e32 v5, v5, v7
	v_lshlrev_b32_e32 v6, 5, v3
	v_ashrrev_i16_sdwa v5, v9, sext(v5) dst_sel:DWORD dst_unused:UNUSED_PAD src0_sel:DWORD src1_sel:BYTE_0
	v_lshlrev_b32_e32 v7, 1, v8
	v_lshrrev_b32_e32 v9, 2, v8
	v_and_b32_e32 v10, 3, v4
	v_and_b32_e32 v6, 32, v6
	v_bfe_i32 v5, v5, 0, 16
	v_and_b32_e32 v7, 24, v7
	v_and_b32_e32 v9, 4, v9
	v_and_or_b32 v10, v8, s1, v10
	v_or3_b32 v7, v10, v9, v7
	v_add_lshl_u32 v6, v6, v5, 1
	v_mad_u64_u32 v[146:147], s[4:5], v8, s8, v[6:7]
	s_lshl_b32 s4, s56, 10
	s_ashr_i32 s0, s48, 6
	s_and_b32 s4, s4, 0x400
	v_mad_u32_u24 v148, v7, s8, v6
	s_ashr_i32 s1, s48, 8
	s_lshl_b32 s5, s0, 10
	s_mulk_i32 s4, 0x1600
	v_readlane_b32 s8, v252, 47
	v_readlane_b32 s9, v252, 48
	s_add_u32 s16, s8, s4
	s_addc_u32 s17, s9, 0
	s_mul_i32 s12, s47, 0x160000
	s_mul_hi_i32 s9, s47, 0x160000
	s_add_u32 s14, s16, s12
	s_addc_u32 s15, s17, s9
	s_add_i32 s34, s5, 16
	s_add_i32 m0, s34, 0x10000
	s_mul_i32 s8, s92, 0x160000
	global_load_lds_dwordx4 v128, s[14:15]
	s_add_i32 m0, s34, 0x12000
	s_mul_hi_i32 s4, s92, 0x160000
	s_add_u32 s18, s94, s8
	global_load_lds_dwordx4 v148, s[14:15]
	s_addc_u32 s19, s95, s4
	s_mov_b32 m0, s34
	s_add_i32 s35, s34, 0x2000
	global_load_lds_dwordx4 v144, s[18:19]
	s_mov_b32 m0, s35
	s_add_u32 s8, s14, 0xb0000
	global_load_lds_dwordx4 v146, s[18:19]
	s_addc_u32 s9, s15, 0
	s_add_i32 m0, s34, 0x14000
	s_nop 0
	global_load_lds_dwordx4 v128, s[8:9]
	s_add_i32 m0, s34, 0x16000
	s_nop 0
	global_load_lds_dwordx4 v148, s[8:9]
	s_add_u32 s8, s18, 0xb0000
	s_addc_u32 s9, s19, 0
	s_add_i32 s36, s34, 0x4000
	s_mov_b32 m0, s36
	s_add_i32 s37, s34, 0x6000
	global_load_lds_dwordx4 v144, s[8:9]
	s_mov_b32 m0, s37
	s_cmp_lg_u32 s1, 1
	global_load_lds_dwordx4 v146, s[8:9]
.LBB0_336:
	v_lshrrev_b32_e32 v15, 1, v141
	v_and_b32_e32 v15, 24, v15
	v_lshl_add_u64 v[6:7], s[14:15], 0, v[128:129]
	v_mov_b32_e32 v149, v129
	v_and_b32_e32 v14, 15, v141
	v_lshlrev_b32_e32 v16, 1, v15
	s_lshl_b32 s0, s0, 5
	v_lshl_add_u64 v[8:9], s[14:15], 0, v[148:149]
	v_mov_b32_e32 v145, v129
	v_lshl_or_b32 v143, s1, 6, v14
	v_lshl_or_b32 v14, v14, 6, v16
	v_lshlrev_b32_e32 v16, 2, v141
	s_and_b32 s4, s0, 0x60
	s_add_i32 m0, s34, 0x18000
	v_lshl_add_u64 v[6:7], v[6:7], 0, s[28:29]
	v_lshl_add_u64 v[10:11], s[18:19], 0, v[144:145]
	v_mov_b32_e32 v147, v129
	s_lshl_b32 s1, s1, 13
	v_and_b32_e32 v16, 32, v16
	s_lshl_b32 s0, s4, 7
	s_waitcnt vmcnt(4)
	s_barrier
	global_load_lds_dwordx4 v[6:7], off
	v_lshl_add_u64 v[6:7], v[8:9], 0, s[28:29]
	s_add_i32 m0, s34, 0x1a000
	s_add_i32 s44, s34, 0x8000
	s_add_i32 s45, s34, 0xa000
	v_lshl_add_u64 v[12:13], s[18:19], 0, v[146:147]
	v_bitop3_b32 v160, s0, v14, v16 bitop3:0xf6
	global_load_lds_dwordx4 v[6:7], off
	v_lshl_add_u64 v[6:7], v[10:11], 0, s[28:29]
	s_mov_b32 m0, s44
	s_add_u32 s0, s14, 0xb0080
	v_bitop3_b32 v17, v14, s1, v16 bitop3:0xde
	global_load_lds_dwordx4 v[6:7], off
	v_lshl_add_u64 v[6:7], v[12:13], 0, s[28:29]
	s_mov_b32 m0, s45
	s_addc_u32 s1, s15, 0
	global_load_lds_dwordx4 v[6:7], off
	s_add_i32 m0, s34, 0x1c000
	v_lshl_add_u64 v[6:7], s[0:1], 0, v[128:129]
	global_load_lds_dwordx4 v[6:7], off
	v_lshl_add_u64 v[6:7], s[0:1], 0, v[148:149]
	s_add_i32 m0, s34, 0x1e000
	s_movk_i32 s8, 0x1600
	global_load_lds_dwordx4 v[6:7], off
	v_or_b32_e32 v161, s4, v15
	v_lshrrev_b32_e32 v7, 1, v0
	v_mul_lo_u32 v6, v1, s8
	s_mov_b32 s4, 0x16000
	v_mad_u64_u32 v[6:7], s[0:1], v7, s4, v[6:7]
	v_and_b32_e32 v0, 1, v0
	v_lshl_or_b32 v0, v0, 6, v6
	v_lshl_add_u32 v150, v2, 1, v0
	v_lshrrev_b32_e32 v1, 1, v3
	v_mul_lo_u32 v0, v4, s8
	v_mad_u64_u32 v[0:1], s[0:1], v1, s4, v[0:1]
	s_waitcnt vmcnt(6)
	v_and_b32_e32 v1, 1, v3
	v_lshl_or_b32 v0, v1, 6, v0
	v_mov_b32_e32 v151, v129
	v_lshl_add_u32 v152, v5, 1, v0
	v_mov_b32_e32 v153, v129
	s_mov_b32 s46, 0
	v_add_u32_e32 v162, 16, v17
	s_barrier
	s_branch .LBB0_338

.LBB0_344:
	s_add_u32 s30, s18, 0xb0080
	s_addc_u32 s31, s19, 0
	s_add_u32 s0, s14, 0x100
	v_mov_b32_e32 v0, 0
	s_addc_u32 s1, s15, 0
	s_mov_b32 s25, -2
	v_mov_b32_e32 v1, v0
	v_mov_b32_e32 v2, v0
	v_mov_b32_e32 v3, v0
	v_mov_b32_e32 v4, v0
	v_mov_b32_e32 v5, v0
	v_mov_b32_e32 v6, v0
	v_mov_b32_e32 v7, v0
	v_mov_b32_e32 v16, v0
	v_mov_b32_e32 v17, v0
	v_mov_b32_e32 v18, v0
	v_mov_b32_e32 v19, v0
	v_mov_b32_e32 v20, v0
	v_mov_b32_e32 v21, v0
	v_mov_b32_e32 v22, v0
	v_mov_b32_e32 v23, v0
	v_mov_b32_e32 v32, v0
	v_mov_b32_e32 v33, v0
	v_mov_b32_e32 v34, v0
	v_mov_b32_e32 v35, v0
	v_mov_b32_e32 v36, v0
	v_mov_b32_e32 v37, v0
	v_mov_b32_e32 v38, v0
	v_mov_b32_e32 v39, v0
	v_mov_b32_e32 v48, v0
	v_mov_b32_e32 v49, v0
	v_mov_b32_e32 v50, v0
	v_mov_b32_e32 v51, v0
	v_mov_b32_e32 v52, v0
	v_mov_b32_e32 v53, v0
	v_mov_b32_e32 v54, v0
	v_mov_b32_e32 v55, v0
	v_mov_b32_e32 v8, v0
	v_mov_b32_e32 v9, v0
	v_mov_b32_e32 v10, v0
	v_mov_b32_e32 v11, v0
	v_mov_b32_e32 v12, v0
	v_mov_b32_e32 v13, v0
	v_mov_b32_e32 v14, v0
	v_mov_b32_e32 v15, v0
	v_mov_b32_e32 v24, v0
	v_mov_b32_e32 v25, v0
	v_mov_b32_e32 v26, v0
	v_mov_b32_e32 v27, v0
	v_mov_b32_e32 v28, v0
	v_mov_b32_e32 v29, v0
	v_mov_b32_e32 v30, v0
	v_mov_b32_e32 v31, v0
	v_mov_b32_e32 v40, v0
	v_mov_b32_e32 v41, v0
	v_mov_b32_e32 v42, v0
	v_mov_b32_e32 v43, v0
	v_mov_b32_e32 v44, v0
	v_mov_b32_e32 v45, v0
	v_mov_b32_e32 v46, v0
	v_mov_b32_e32 v47, v0
	v_mov_b32_e32 v56, v0
	v_mov_b32_e32 v57, v0
	v_mov_b32_e32 v58, v0
	v_mov_b32_e32 v59, v0
	v_mov_b32_e32 v60, v0
	v_mov_b32_e32 v61, v0
	v_mov_b32_e32 v62, v0
	v_mov_b32_e32 v63, v0
	v_mov_b32_e32 v64, v0
	v_mov_b32_e32 v65, v0
	v_mov_b32_e32 v66, v0
	v_mov_b32_e32 v67, v0
	v_mov_b32_e32 v68, v0
	v_mov_b32_e32 v69, v0
	v_mov_b32_e32 v70, v0
	v_mov_b32_e32 v71, v0
	v_mov_b32_e32 v80, v0
	v_mov_b32_e32 v81, v0
	v_mov_b32_e32 v82, v0
	v_mov_b32_e32 v83, v0
	v_mov_b32_e32 v84, v0
	v_mov_b32_e32 v85, v0
	v_mov_b32_e32 v86, v0
	v_mov_b32_e32 v87, v0
	v_mov_b32_e32 v96, v0
	v_mov_b32_e32 v97, v0
	v_mov_b32_e32 v98, v0
	v_mov_b32_e32 v99, v0
	v_mov_b32_e32 v100, v0
	v_mov_b32_e32 v101, v0
	v_mov_b32_e32 v102, v0
	v_mov_b32_e32 v103, v0
	v_mov_b32_e32 v112, v0
	v_mov_b32_e32 v113, v0
	v_mov_b32_e32 v114, v0
	v_mov_b32_e32 v115, v0
	v_mov_b32_e32 v116, v0
	v_mov_b32_e32 v117, v0
	v_mov_b32_e32 v118, v0
	v_mov_b32_e32 v119, v0
	v_mov_b32_e32 v72, v0
	v_mov_b32_e32 v73, v0
	v_mov_b32_e32 v74, v0
	v_mov_b32_e32 v75, v0
	v_mov_b32_e32 v76, v0
	v_mov_b32_e32 v77, v0
	v_mov_b32_e32 v78, v0
	v_mov_b32_e32 v79, v0
	v_mov_b32_e32 v88, v0
	v_mov_b32_e32 v89, v0
	v_mov_b32_e32 v90, v0
	v_mov_b32_e32 v91, v0
	v_mov_b32_e32 v92, v0
	v_mov_b32_e32 v93, v0
	v_mov_b32_e32 v94, v0
	v_mov_b32_e32 v95, v0
	v_mov_b32_e32 v104, v0
	v_mov_b32_e32 v105, v0
	v_mov_b32_e32 v106, v0
	v_mov_b32_e32 v107, v0
	v_mov_b32_e32 v108, v0
	v_mov_b32_e32 v109, v0
	v_mov_b32_e32 v110, v0
	v_mov_b32_e32 v111, v0
	v_mov_b32_e32 v120, v0
	v_mov_b32_e32 v121, v0
	v_mov_b32_e32 v122, v0
	v_mov_b32_e32 v123, v0
	v_mov_b32_e32 v124, v0
	v_mov_b32_e32 v125, v0
	v_mov_b32_e32 v126, v0
	v_mov_b32_e32 v127, v0
	s_cmpk_gt_u32 s48, 0xff
	s_cbranch_scc0 .Lg2_enter
	s_barrier
.Lg2_enter:
.LBB0_345:
	s_add_u32 s14, s30, 0xfff50080
	s_addc_u32 s15, s31, -1
	s_add_i32 s20, 16, 0x10000
	v_add_u32_e32 v130, s20, v160
	ds_read_b128 v[154:157], v130
	ds_read_b128 v[164:167], v130 offset:1024
	ds_read_b128 v[168:171], v130 offset:2048
	ds_read_b128 v[172:175], v130 offset:3072
	s_cmp_eq_u32 s25, 40
	s_cselect_b32 s19, s9, s15
	s_cselect_b32 s18, s8, s14
	s_cselect_b32 s15, s13, s1
	s_cselect_b32 s14, s12, s0
	v_lshl_add_u64 v[130:131], s[30:31], 0, v[150:151]
	s_add_i32 m0, s34, 0xc000
	ds_read_b128 v[176:179], v162
	ds_read_b128 v[180:183], v162 offset:1024
	ds_read_b128 v[184:187], v162 offset:2048
	ds_read_b128 v[188:191], v162 offset:3072
	ds_read_b128 v[192:195], v162 offset:4096
	ds_read_b128 v[196:199], v162 offset:5120
	ds_read_b128 v[200:203], v162 offset:6144
	ds_read_b128 v[204:207], v162 offset:7168
	global_load_lds_dwordx4 v[130:131], off
	v_lshl_add_u64 v[130:131], s[30:31], 0, v[152:153]
	s_add_i32 m0, s34, 0xe000
	s_nop 0
	global_load_lds_dwordx4 v[130:131], off
	s_add_i32 s42, 16, 0x14000
	v_add_u32_e32 v130, s42, v160
	ds_read_b128 v[208:211], v130
	ds_read_b128 v[212:215], v130 offset:1024
	ds_read_b128 v[216:219], v130 offset:2048
	ds_read_b128 v[220:223], v130 offset:3072
	s_waitcnt vmcnt(8) lgkmcnt(0)
	s_barrier
	s_setprio 1
	v_mfma_f32_16x16x32_bf16 v[124:127], v[154:157], v[176:179], v[124:127]
	v_mfma_f32_16x16x32_bf16 v[120:123], v[168:171], v[176:179], v[120:123]
	v_mfma_f32_16x16x32_bf16 v[108:111], v[154:157], v[184:187], v[108:111]
	v_mfma_f32_16x16x32_bf16 v[104:107], v[168:171], v[184:187], v[104:107]
	v_mfma_f32_16x16x32_bf16 v[92:95], v[154:157], v[192:195], v[92:95]
	v_mfma_f32_16x16x32_bf16 v[88:91], v[168:171], v[192:195], v[88:91]
	v_mfma_f32_16x16x32_bf16 v[76:79], v[154:157], v[200:203], v[76:79]
	v_mfma_f32_16x16x32_bf16 v[72:75], v[168:171], v[200:203], v[72:75]
	v_mfma_f32_16x16x32_bf16 v[124:127], v[164:167], v[180:183], v[124:127]
	v_mfma_f32_16x16x32_bf16 v[120:123], v[172:175], v[180:183], v[120:123]
	v_mfma_f32_16x16x32_bf16 v[108:111], v[164:167], v[188:191], v[108:111]
	v_mfma_f32_16x16x32_bf16 v[104:107], v[172:175], v[188:191], v[104:107]
	v_mfma_f32_16x16x32_bf16 v[92:95], v[164:167], v[196:199], v[92:95]
	v_mfma_f32_16x16x32_bf16 v[88:91], v[172:175], v[196:199], v[88:91]
	v_mfma_f32_16x16x32_bf16 v[76:79], v[164:167], v[204:207], v[76:79]
	v_mfma_f32_16x16x32_bf16 v[72:75], v[172:175], v[204:207], v[72:75]
	v_mfma_f32_16x16x32_bf16 v[116:119], v[208:211], v[176:179], v[116:119]
	v_mfma_f32_16x16x32_bf16 v[112:115], v[216:219], v[176:179], v[112:115]
	v_mfma_f32_16x16x32_bf16 v[100:103], v[208:211], v[184:187], v[100:103]
	v_mfma_f32_16x16x32_bf16 v[96:99], v[216:219], v[184:187], v[96:99]
	v_mfma_f32_16x16x32_bf16 v[84:87], v[208:211], v[192:195], v[84:87]
	v_mfma_f32_16x16x32_bf16 v[80:83], v[216:219], v[192:195], v[80:83]
	v_mfma_f32_16x16x32_bf16 v[68:71], v[208:211], v[200:203], v[68:71]
	v_mfma_f32_16x16x32_bf16 v[64:67], v[216:219], v[200:203], v[64:67]
	v_mfma_f32_16x16x32_bf16 v[116:119], v[212:215], v[180:183], v[116:119]
	v_mfma_f32_16x16x32_bf16 v[112:115], v[220:223], v[180:183], v[112:115]
	v_mfma_f32_16x16x32_bf16 v[100:103], v[212:215], v[188:191], v[100:103]
	v_mfma_f32_16x16x32_bf16 v[96:99], v[220:223], v[188:191], v[96:99]
	v_mfma_f32_16x16x32_bf16 v[84:87], v[212:215], v[196:199], v[84:87]
	v_mfma_f32_16x16x32_bf16 v[80:83], v[220:223], v[196:199], v[80:83]
	v_mfma_f32_16x16x32_bf16 v[68:71], v[212:215], v[204:207], v[68:71]
	v_mfma_f32_16x16x32_bf16 v[64:67], v[220:223], v[204:207], v[64:67]
	s_setprio 0
	s_barrier
	ds_read_b128 v[176:179], v162 offset:16384
	ds_read_b128 v[180:183], v162 offset:17408
	ds_read_b128 v[184:187], v162 offset:18432
	ds_read_b128 v[188:191], v162 offset:19456
	ds_read_b128 v[192:195], v162 offset:20480
	ds_read_b128 v[196:199], v162 offset:21504
	ds_read_b128 v[200:203], v162 offset:22528
	ds_read_b128 v[204:207], v162 offset:23552
	s_add_i32 s20, s20, s5
	v_lshl_add_u64 v[130:131], s[14:15], 0, v[128:129]
	s_mov_b32 m0, s20
	v_lshl_add_u64 v[132:133], s[14:15], 0, v[148:149]
	global_load_lds_dwordx4 v[130:131], off
	s_add_i32 m0, s20, 0x2000
	s_nop 0
	global_load_lds_dwordx4 v[132:133], off
	s_mov_b32 m0, s34
	v_lshl_add_u64 v[134:135], s[18:19], 0, v[144:145]
	global_load_lds_dwordx4 v[134:135], off
	v_lshl_add_u64 v[136:137], s[18:19], 0, v[146:147]
	s_mov_b32 m0, s35
	s_nop 0
	global_load_lds_dwordx4 v[136:137], off
	s_add_u32 s40, s14, 0xb0000
	s_addc_u32 s41, s15, 0
	s_add_i32 s20, s42, s5
	v_lshl_add_u64 v[138:139], s[40:41], 0, v[128:129]
	s_mov_b32 m0, s20
	s_nop 0
	global_load_lds_dwordx4 v[138:139], off
	v_lshl_add_u64 v[138:139], s[40:41], 0, v[148:149]
	s_add_i32 m0, s20, 0x2000
	s_nop 0
	global_load_lds_dwordx4 v[138:139], off
	s_waitcnt vmcnt(8) lgkmcnt(0)
	s_barrier
	s_setprio 1
	v_mfma_f32_16x16x32_bf16 v[60:63], v[154:157], v[176:179], v[60:63]
	v_mfma_f32_16x16x32_bf16 v[56:59], v[168:171], v[176:179], v[56:59]
	v_mfma_f32_16x16x32_bf16 v[44:47], v[154:157], v[184:187], v[44:47]
	v_mfma_f32_16x16x32_bf16 v[40:43], v[168:171], v[184:187], v[40:43]
	v_mfma_f32_16x16x32_bf16 v[28:31], v[154:157], v[192:195], v[28:31]
	v_mfma_f32_16x16x32_bf16 v[24:27], v[168:171], v[192:195], v[24:27]
	v_mfma_f32_16x16x32_bf16 v[12:15], v[154:157], v[200:203], v[12:15]
	v_mfma_f32_16x16x32_bf16 v[8:11], v[168:171], v[200:203], v[8:11]
	v_mfma_f32_16x16x32_bf16 v[60:63], v[164:167], v[180:183], v[60:63]
	v_mfma_f32_16x16x32_bf16 v[56:59], v[172:175], v[180:183], v[56:59]
	v_mfma_f32_16x16x32_bf16 v[44:47], v[164:167], v[188:191], v[44:47]
	v_mfma_f32_16x16x32_bf16 v[40:43], v[172:175], v[188:191], v[40:43]
	v_mfma_f32_16x16x32_bf16 v[28:31], v[164:167], v[196:199], v[28:31]
	v_mfma_f32_16x16x32_bf16 v[24:27], v[172:175], v[196:199], v[24:27]
	v_mfma_f32_16x16x32_bf16 v[12:15], v[164:167], v[204:207], v[12:15]
	v_mfma_f32_16x16x32_bf16 v[8:11], v[172:175], v[204:207], v[8:11]
	v_mfma_f32_16x16x32_bf16 v[52:55], v[208:211], v[176:179], v[52:55]
	v_mfma_f32_16x16x32_bf16 v[48:51], v[216:219], v[176:179], v[48:51]
	v_mfma_f32_16x16x32_bf16 v[36:39], v[208:211], v[184:187], v[36:39]
	v_mfma_f32_16x16x32_bf16 v[32:35], v[216:219], v[184:187], v[32:35]
	v_mfma_f32_16x16x32_bf16 v[20:23], v[208:211], v[192:195], v[20:23]
	v_mfma_f32_16x16x32_bf16 v[16:19], v[216:219], v[192:195], v[16:19]
	v_mfma_f32_16x16x32_bf16 v[4:7], v[208:211], v[200:203], v[4:7]
	v_mfma_f32_16x16x32_bf16 v[0:3], v[216:219], v[200:203], v[0:3]
	v_mfma_f32_16x16x32_bf16 v[52:55], v[212:215], v[180:183], v[52:55]
	v_mfma_f32_16x16x32_bf16 v[48:51], v[220:223], v[180:183], v[48:51]
	v_mfma_f32_16x16x32_bf16 v[36:39], v[212:215], v[188:191], v[36:39]
	v_mfma_f32_16x16x32_bf16 v[32:35], v[220:223], v[188:191], v[32:35]
	v_mfma_f32_16x16x32_bf16 v[20:23], v[212:215], v[196:199], v[20:23]
	v_mfma_f32_16x16x32_bf16 v[16:19], v[220:223], v[196:199], v[16:19]
	v_mfma_f32_16x16x32_bf16 v[4:7], v[212:215], v[204:207], v[4:7]
	v_mfma_f32_16x16x32_bf16 v[0:3], v[220:223], v[204:207], v[0:3]
	s_setprio 0
	s_add_i32 s20, 16, 0x18000
	v_add_u32_e32 v138, s20, v160
	s_barrier
	ds_read_b128 v[154:157], v138
	ds_read_b128 v[164:167], v138 offset:1024
	ds_read_b128 v[168:171], v138 offset:2048
	ds_read_b128 v[172:175], v138 offset:3072
	s_add_u32 s18, s18, 0xb0000
	s_addc_u32 s19, s19, 0
	s_mov_b32 m0, s36
	v_lshl_add_u64 v[158:159], s[18:19], 0, v[144:145]
	ds_read_b128 v[176:179], v162 offset:32768
	ds_read_b128 v[180:183], v162 offset:33792
	ds_read_b128 v[184:187], v162 offset:34816
	ds_read_b128 v[188:191], v162 offset:35840
	ds_read_b128 v[192:195], v162 offset:36864
	ds_read_b128 v[196:199], v162 offset:37888
	ds_read_b128 v[200:203], v162 offset:38912
	ds_read_b128 v[204:207], v162 offset:39936
	global_load_lds_dwordx4 v[158:159], off
	v_lshl_add_u64 v[158:159], s[18:19], 0, v[146:147]
	s_mov_b32 m0, s37
	s_nop 0
	global_load_lds_dwordx4 v[158:159], off
	s_add_i32 s18, 16, 0x1c000
	v_add_u32_e32 v138, s18, v160
	ds_read_b128 v[208:211], v138
	ds_read_b128 v[212:215], v138 offset:1024
	ds_read_b128 v[216:219], v138 offset:2048
	ds_read_b128 v[220:223], v138 offset:3072
	s_waitcnt vmcnt(8) lgkmcnt(0)
	s_barrier
	s_setprio 1
	v_mfma_f32_16x16x32_bf16 v[124:127], v[154:157], v[176:179], v[124:127]
	v_mfma_f32_16x16x32_bf16 v[120:123], v[168:171], v[176:179], v[120:123]
	v_mfma_f32_16x16x32_bf16 v[108:111], v[154:157], v[184:187], v[108:111]
	v_mfma_f32_16x16x32_bf16 v[104:107], v[168:171], v[184:187], v[104:107]
	v_mfma_f32_16x16x32_bf16 v[92:95], v[154:157], v[192:195], v[92:95]
	v_mfma_f32_16x16x32_bf16 v[88:91], v[168:171], v[192:195], v[88:91]
	v_mfma_f32_16x16x32_bf16 v[76:79], v[154:157], v[200:203], v[76:79]
	v_mfma_f32_16x16x32_bf16 v[72:75], v[168:171], v[200:203], v[72:75]
	v_mfma_f32_16x16x32_bf16 v[124:127], v[164:167], v[180:183], v[124:127]
	v_mfma_f32_16x16x32_bf16 v[120:123], v[172:175], v[180:183], v[120:123]
	v_mfma_f32_16x16x32_bf16 v[108:111], v[164:167], v[188:191], v[108:111]
	v_mfma_f32_16x16x32_bf16 v[104:107], v[172:175], v[188:191], v[104:107]
	v_mfma_f32_16x16x32_bf16 v[92:95], v[164:167], v[196:199], v[92:95]
	v_mfma_f32_16x16x32_bf16 v[88:91], v[172:175], v[196:199], v[88:91]
	v_mfma_f32_16x16x32_bf16 v[76:79], v[164:167], v[204:207], v[76:79]
	v_mfma_f32_16x16x32_bf16 v[72:75], v[172:175], v[204:207], v[72:75]
	v_mfma_f32_16x16x32_bf16 v[116:119], v[208:211], v[176:179], v[116:119]
	v_mfma_f32_16x16x32_bf16 v[112:115], v[216:219], v[176:179], v[112:115]
	v_mfma_f32_16x16x32_bf16 v[100:103], v[208:211], v[184:187], v[100:103]
	v_mfma_f32_16x16x32_bf16 v[96:99], v[216:219], v[184:187], v[96:99]
	v_mfma_f32_16x16x32_bf16 v[84:87], v[208:211], v[192:195], v[84:87]
	v_mfma_f32_16x16x32_bf16 v[80:83], v[216:219], v[192:195], v[80:83]
	v_mfma_f32_16x16x32_bf16 v[68:71], v[208:211], v[200:203], v[68:71]
	v_mfma_f32_16x16x32_bf16 v[64:67], v[216:219], v[200:203], v[64:67]
	v_mfma_f32_16x16x32_bf16 v[116:119], v[212:215], v[180:183], v[116:119]
	v_mfma_f32_16x16x32_bf16 v[112:115], v[220:223], v[180:183], v[112:115]
	v_mfma_f32_16x16x32_bf16 v[100:103], v[212:215], v[188:191], v[100:103]
	v_mfma_f32_16x16x32_bf16 v[96:99], v[220:223], v[188:191], v[96:99]
	v_mfma_f32_16x16x32_bf16 v[84:87], v[212:215], v[196:199], v[84:87]
	v_mfma_f32_16x16x32_bf16 v[80:83], v[220:223], v[196:199], v[80:83]
	v_mfma_f32_16x16x32_bf16 v[68:71], v[212:215], v[204:207], v[68:71]
	v_mfma_f32_16x16x32_bf16 v[64:67], v[220:223], v[204:207], v[64:67]
	s_setprio 0
	s_barrier
	ds_read_b128 v[176:179], v162 offset:49152
	ds_read_b128 v[180:183], v162 offset:50176
	ds_read_b128 v[184:187], v162 offset:51200
	ds_read_b128 v[188:191], v162 offset:52224
	ds_read_b128 v[192:195], v162 offset:53248
	ds_read_b128 v[196:199], v162 offset:54272
	ds_read_b128 v[200:203], v162 offset:55296
	ds_read_b128 v[204:207], v162 offset:56320
	s_add_i32 s19, s20, s5
	v_lshl_add_u64 v[130:131], v[130:131], 0, s[28:29]
	s_mov_b32 m0, s19
	s_nop 0
	global_load_lds_dwordx4 v[130:131], off
	v_lshl_add_u64 v[130:131], v[132:133], 0, s[28:29]
	s_add_i32 m0, s19, 0x2000
	s_nop 0
	global_load_lds_dwordx4 v[130:131], off
	s_mov_b32 m0, s44
	v_lshl_add_u64 v[130:131], v[134:135], 0, s[28:29]
	global_load_lds_dwordx4 v[130:131], off
	v_lshl_add_u64 v[130:131], v[136:137], 0, s[28:29]
	s_mov_b32 m0, s45
	s_nop 0
	global_load_lds_dwordx4 v[130:131], off
	s_add_u32 s14, s14, 0xb0080
	s_addc_u32 s15, s15, 0
	s_add_i32 s18, s18, s5
	v_lshl_add_u64 v[130:131], s[14:15], 0, v[128:129]
	s_mov_b32 m0, s18
	s_nop 0
	global_load_lds_dwordx4 v[130:131], off
	v_lshl_add_u64 v[130:131], s[14:15], 0, v[148:149]
	s_add_i32 m0, s18, 0x2000
	s_nop 0
	global_load_lds_dwordx4 v[130:131], off
	s_waitcnt vmcnt(8) lgkmcnt(0)
	s_barrier
	s_setprio 1
	v_mfma_f32_16x16x32_bf16 v[60:63], v[154:157], v[176:179], v[60:63]
	v_mfma_f32_16x16x32_bf16 v[56:59], v[168:171], v[176:179], v[56:59]
	v_mfma_f32_16x16x32_bf16 v[44:47], v[154:157], v[184:187], v[44:47]
	v_mfma_f32_16x16x32_bf16 v[40:43], v[168:171], v[184:187], v[40:43]
	v_mfma_f32_16x16x32_bf16 v[28:31], v[154:157], v[192:195], v[28:31]
	v_mfma_f32_16x16x32_bf16 v[24:27], v[168:171], v[192:195], v[24:27]
	v_mfma_f32_16x16x32_bf16 v[12:15], v[154:157], v[200:203], v[12:15]
	v_mfma_f32_16x16x32_bf16 v[8:11], v[168:171], v[200:203], v[8:11]
	v_mfma_f32_16x16x32_bf16 v[60:63], v[164:167], v[180:183], v[60:63]
	v_mfma_f32_16x16x32_bf16 v[56:59], v[172:175], v[180:183], v[56:59]
	v_mfma_f32_16x16x32_bf16 v[44:47], v[164:167], v[188:191], v[44:47]
	v_mfma_f32_16x16x32_bf16 v[40:43], v[172:175], v[188:191], v[40:43]
	v_mfma_f32_16x16x32_bf16 v[28:31], v[164:167], v[196:199], v[28:31]
	v_mfma_f32_16x16x32_bf16 v[24:27], v[172:175], v[196:199], v[24:27]
	v_mfma_f32_16x16x32_bf16 v[12:15], v[164:167], v[204:207], v[12:15]
	v_mfma_f32_16x16x32_bf16 v[8:11], v[172:175], v[204:207], v[8:11]
	v_mfma_f32_16x16x32_bf16 v[52:55], v[208:211], v[176:179], v[52:55]
	v_mfma_f32_16x16x32_bf16 v[48:51], v[216:219], v[176:179], v[48:51]
	v_mfma_f32_16x16x32_bf16 v[36:39], v[208:211], v[184:187], v[36:39]
	v_mfma_f32_16x16x32_bf16 v[32:35], v[216:219], v[184:187], v[32:35]
	v_mfma_f32_16x16x32_bf16 v[20:23], v[208:211], v[192:195], v[20:23]
	v_mfma_f32_16x16x32_bf16 v[16:19], v[216:219], v[192:195], v[16:19]
	v_mfma_f32_16x16x32_bf16 v[4:7], v[208:211], v[200:203], v[4:7]
	v_mfma_f32_16x16x32_bf16 v[0:3], v[216:219], v[200:203], v[0:3]
	v_mfma_f32_16x16x32_bf16 v[52:55], v[212:215], v[180:183], v[52:55]
	v_mfma_f32_16x16x32_bf16 v[48:51], v[220:223], v[180:183], v[48:51]
	v_mfma_f32_16x16x32_bf16 v[36:39], v[212:215], v[188:191], v[36:39]
	v_mfma_f32_16x16x32_bf16 v[32:35], v[220:223], v[188:191], v[32:35]
	v_mfma_f32_16x16x32_bf16 v[20:23], v[212:215], v[196:199], v[20:23]
	v_mfma_f32_16x16x32_bf16 v[16:19], v[220:223], v[196:199], v[16:19]
	v_mfma_f32_16x16x32_bf16 v[4:7], v[212:215], v[204:207], v[4:7]
	v_mfma_f32_16x16x32_bf16 v[0:3], v[220:223], v[204:207], v[0:3]
	s_setprio 0
	s_add_i32 s25, s25, 2
	s_add_u32 s30, s30, 0x100
	s_addc_u32 s31, s31, 0
	s_add_u32 s0, s0, 0x100
	s_addc_u32 s1, s1, 0
	s_cmp_gt_u32 s25, 41
	s_cbranch_scc1 .Lg2_exit
	s_barrier
	s_branch .LBB0_345

.Lg2_epi:
	s_cmp_lt_i32 s47, 0
	s_cselect_b64 s[14:15], -1, 0
	s_cmp_gt_i32 s47, -1
	s_cbranch_scc1 .LBB0_348
	v_mul_f32_e32 v131, 0x3d372713, v120
	v_mul_f32_e32 v131, v120, v131
	v_fma_f32 v131, v120, v131, v120
	v_mul_f32_e32 v131, 0x3fcc422a, v131
	v_mul_f32_e32 v131, 0xbfb8aa3b, v131
	v_exp_f32_e32 v131, v131
	v_mul_f32_e32 v130, 0x3d372713, v124
	v_mul_f32_e32 v130, v124, v130
	v_fma_f32 v130, v124, v130, v124
	v_add_f32_e32 v131, 1.0, v131
	v_rcp_f32_e32 v132, v131
	v_mul_f32_e32 v131, 0x3d372713, v125
	v_mul_f32_e32 v131, v125, v131
	v_fma_f32 v131, v125, v131, v125
	v_mul_f32_e32 v130, 0x3fcc422a, v130
	v_mul_f32_e32 v131, 0x3fcc422a, v131
	v_mul_f32_e32 v130, 0xbfb8aa3b, v130
	v_mul_f32_e32 v131, 0xbfb8aa3b, v131
	v_mul_f32_e32 v135, 0x3d372713, v122
	v_exp_f32_e32 v130, v130
	v_exp_f32_e32 v131, v131
	v_mul_f32_e32 v135, v122, v135
	v_fma_f32 v135, v122, v135, v122
	v_mul_f32_e32 v135, 0x3fcc422a, v135
	v_mul_f32_e32 v135, 0xbfb8aa3b, v135
	v_add_f32_e32 v130, 1.0, v130
	v_add_f32_e32 v131, 1.0, v131
	v_exp_f32_e32 v135, v135
	v_rcp_f32_e32 v130, v130
	v_rcp_f32_e32 v131, v131
	v_mul_f32_e32 v133, 0x3d372713, v121
	v_add_f32_e32 v135, 1.0, v135
	v_mul_f32_e32 v134, 0x3d372713, v126
	v_rcp_f32_e32 v136, v135
	v_mul_f32_e32 v135, 0x3d372713, v127
	v_pk_mul_f32 v[124:125], v[124:125], v[130:131]
	v_mul_f32_e32 v130, 0x3d372713, v123
	v_mul_f32_e32 v133, v121, v133
	v_mul_f32_e32 v134, v126, v134
	v_mul_f32_e32 v135, v127, v135
	v_mul_f32_e32 v130, v123, v130
	v_fma_f32 v133, v121, v133, v121
	v_fma_f32 v134, v126, v134, v126
	v_fma_f32 v135, v127, v135, v127
	v_fma_f32 v130, v123, v130, v123
	v_mul_f32_e32 v133, 0x3fcc422a, v133
	v_mul_f32_e32 v134, 0x3fcc422a, v134
	v_mul_f32_e32 v135, 0x3fcc422a, v135
	v_mul_f32_e32 v130, 0x3fcc422a, v130
	v_mul_f32_e32 v133, 0xbfb8aa3b, v133
	v_mul_f32_e32 v134, 0xbfb8aa3b, v134
	v_mul_f32_e32 v135, 0xbfb8aa3b, v135
	v_mul_f32_e32 v130, 0xbfb8aa3b, v130
	v_exp_f32_e32 v133, v133
	v_exp_f32_e32 v134, v134
	v_exp_f32_e32 v135, v135
	v_exp_f32_e32 v130, v130
	v_add_f32_e32 v133, 1.0, v133
	v_add_f32_e32 v134, 1.0, v134
	v_add_f32_e32 v135, 1.0, v135
	v_add_f32_e32 v130, 1.0, v130
	v_rcp_f32_e32 v133, v133
	v_rcp_f32_e32 v134, v134
	v_rcp_f32_e32 v135, v135
	v_rcp_f32_e32 v137, v130
	v_pk_mul_f32 v[120:121], v[120:121], v[132:133]
	v_pk_mul_f32 v[126:127], v[126:127], v[134:135]
	v_pk_mul_f32 v[122:123], v[122:123], v[136:137]

.LBB0_378:
	s_waitcnt vmcnt(0)
	v_readlane_b32 s24, v255, 23
	v_readlane_b32 s25, v255, 24

.Lg1_enter:
.LBB0_391:
	s_add_u32 s14, s30, 0xfffc0080
	s_addc_u32 s15, s31, -1
	s_add_i32 s20, 16, 0x10000
	v_add_u32_e32 v130, s20, v156
	ds_read_b128 v[166:169], v130
	ds_read_b128 v[170:173], v130 offset:1024
	ds_read_b128 v[174:177], v130 offset:2048
	ds_read_b128 v[178:181], v130 offset:3072
	s_cmp_eq_u32 s92, 12
	s_cselect_b32 s19, s1, s15
	s_cselect_b32 s18, s13, s14
	s_cselect_b32 s15, s9, s47
	s_cselect_b32 s14, s24, s25
	v_lshl_add_u64 v[130:131], s[30:31], 0, v[150:151]
	s_add_i32 m0, s34, 0xc000
	ds_read_b128 v[182:185], v158
	ds_read_b128 v[186:189], v158 offset:1024
	ds_read_b128 v[190:193], v158 offset:2048
	ds_read_b128 v[194:197], v158 offset:3072
	ds_read_b128 v[198:201], v158 offset:4096
	ds_read_b128 v[202:205], v158 offset:5120
	ds_read_b128 v[206:209], v158 offset:6144
	ds_read_b128 v[210:213], v158 offset:7168
	global_load_lds_dwordx4 v[130:131], off
	v_lshl_add_u64 v[130:131], s[30:31], 0, v[152:153]
	s_add_i32 m0, s34, 0xe000
	s_nop 0
	global_load_lds_dwordx4 v[130:131], off
	s_add_i32 s50, 16, 0x14000
	v_add_u32_e32 v130, s50, v156
	ds_read_b128 v[214:217], v130
	ds_read_b128 v[218:221], v130 offset:1024
	ds_read_b128 v[222:225], v130 offset:2048
	ds_read_b128 v[226:229], v130 offset:3072
	s_waitcnt vmcnt(8) lgkmcnt(0)
	s_barrier
	s_setprio 1
	v_mfma_f32_16x16x32_bf16 v[116:119], v[166:169], v[182:185], v[116:119]
	v_mfma_f32_16x16x32_bf16 v[112:115], v[174:177], v[182:185], v[112:115]
	v_mfma_f32_16x16x32_bf16 v[100:103], v[166:169], v[190:193], v[100:103]
	v_mfma_f32_16x16x32_bf16 v[96:99], v[174:177], v[190:193], v[96:99]
	v_mfma_f32_16x16x32_bf16 v[84:87], v[166:169], v[198:201], v[84:87]
	v_mfma_f32_16x16x32_bf16 v[80:83], v[174:177], v[198:201], v[80:83]
	v_mfma_f32_16x16x32_bf16 v[68:71], v[166:169], v[206:209], v[68:71]
	v_mfma_f32_16x16x32_bf16 v[64:67], v[174:177], v[206:209], v[64:67]
	v_mfma_f32_16x16x32_bf16 v[116:119], v[170:173], v[186:189], v[116:119]
	v_mfma_f32_16x16x32_bf16 v[112:115], v[178:181], v[186:189], v[112:115]
	v_mfma_f32_16x16x32_bf16 v[100:103], v[170:173], v[194:197], v[100:103]
	v_mfma_f32_16x16x32_bf16 v[96:99], v[178:181], v[194:197], v[96:99]
	v_mfma_f32_16x16x32_bf16 v[84:87], v[170:173], v[202:205], v[84:87]
	v_mfma_f32_16x16x32_bf16 v[80:83], v[178:181], v[202:205], v[80:83]
	v_mfma_f32_16x16x32_bf16 v[68:71], v[170:173], v[210:213], v[68:71]
	v_mfma_f32_16x16x32_bf16 v[64:67], v[178:181], v[210:213], v[64:67]
	v_mfma_f32_16x16x32_bf16 v[124:127], v[214:217], v[182:185], v[124:127]
	v_mfma_f32_16x16x32_bf16 v[120:123], v[222:225], v[182:185], v[120:123]
	v_mfma_f32_16x16x32_bf16 v[108:111], v[214:217], v[190:193], v[108:111]
	v_mfma_f32_16x16x32_bf16 v[104:107], v[222:225], v[190:193], v[104:107]
	v_mfma_f32_16x16x32_bf16 v[92:95], v[214:217], v[198:201], v[92:95]
	v_mfma_f32_16x16x32_bf16 v[88:91], v[222:225], v[198:201], v[88:91]
	v_mfma_f32_16x16x32_bf16 v[76:79], v[214:217], v[206:209], v[76:79]
	v_mfma_f32_16x16x32_bf16 v[72:75], v[222:225], v[206:209], v[72:75]
	v_mfma_f32_16x16x32_bf16 v[124:127], v[218:221], v[186:189], v[124:127]
	v_mfma_f32_16x16x32_bf16 v[120:123], v[226:229], v[186:189], v[120:123]
	v_mfma_f32_16x16x32_bf16 v[108:111], v[218:221], v[194:197], v[108:111]
	v_mfma_f32_16x16x32_bf16 v[104:107], v[226:229], v[194:197], v[104:107]
	v_mfma_f32_16x16x32_bf16 v[92:95], v[218:221], v[202:205], v[92:95]
	v_mfma_f32_16x16x32_bf16 v[88:91], v[226:229], v[202:205], v[88:91]
	v_mfma_f32_16x16x32_bf16 v[76:79], v[218:221], v[210:213], v[76:79]
	v_mfma_f32_16x16x32_bf16 v[72:75], v[226:229], v[210:213], v[72:75]
	s_setprio 0
	s_barrier
	ds_read_b128 v[182:185], v158 offset:16384
	ds_read_b128 v[186:189], v158 offset:17408
	ds_read_b128 v[190:193], v158 offset:18432
	ds_read_b128 v[194:197], v158 offset:19456
	ds_read_b128 v[198:201], v158 offset:20480
	ds_read_b128 v[202:205], v158 offset:21504
	ds_read_b128 v[206:209], v158 offset:22528
	ds_read_b128 v[210:213], v158 offset:23552
	s_add_i32 s20, s20, s5
	v_lshl_add_u64 v[130:131], s[14:15], 0, v[128:129]
	s_mov_b32 m0, s20
	v_lshl_add_u64 v[132:133], s[14:15], 0, v[144:145]
	global_load_lds_dwordx4 v[130:131], off
	s_add_i32 m0, s20, 0x2000
	s_nop 0
	global_load_lds_dwordx4 v[132:133], off
	s_mov_b32 m0, s34
	v_lshl_add_u64 v[134:135], s[18:19], 0, v[148:149]
	global_load_lds_dwordx4 v[134:135], off
	v_lshl_add_u64 v[136:137], s[18:19], 0, v[146:147]
	s_mov_b32 m0, s35
	s_nop 0
	global_load_lds_dwordx4 v[136:137], off
	s_add_u32 s48, s14, 0x40000
	s_addc_u32 s49, s15, 0
	s_add_i32 s20, s50, s5
	v_lshl_add_u64 v[138:139], s[48:49], 0, v[128:129]
	s_mov_b32 m0, s20
	s_nop 0
	global_load_lds_dwordx4 v[138:139], off
	v_lshl_add_u64 v[138:139], s[48:49], 0, v[144:145]
	s_add_i32 m0, s20, 0x2000
	s_nop 0
	global_load_lds_dwordx4 v[138:139], off
	s_waitcnt vmcnt(8) lgkmcnt(0)
	s_barrier
	s_setprio 1
	v_mfma_f32_16x16x32_bf16 v[52:55], v[166:169], v[182:185], v[52:55]
	v_mfma_f32_16x16x32_bf16 v[48:51], v[174:177], v[182:185], v[48:51]
	v_mfma_f32_16x16x32_bf16 v[36:39], v[166:169], v[190:193], v[36:39]
	v_mfma_f32_16x16x32_bf16 v[32:35], v[174:177], v[190:193], v[32:35]
	v_mfma_f32_16x16x32_bf16 v[20:23], v[166:169], v[198:201], v[20:23]
	v_mfma_f32_16x16x32_bf16 v[16:19], v[174:177], v[198:201], v[16:19]
	v_mfma_f32_16x16x32_bf16 v[4:7], v[166:169], v[206:209], v[4:7]
	v_mfma_f32_16x16x32_bf16 v[0:3], v[174:177], v[206:209], v[0:3]
	v_mfma_f32_16x16x32_bf16 v[52:55], v[170:173], v[186:189], v[52:55]
	v_mfma_f32_16x16x32_bf16 v[48:51], v[178:181], v[186:189], v[48:51]
	v_mfma_f32_16x16x32_bf16 v[36:39], v[170:173], v[194:197], v[36:39]
	v_mfma_f32_16x16x32_bf16 v[32:35], v[178:181], v[194:197], v[32:35]
	v_mfma_f32_16x16x32_bf16 v[20:23], v[170:173], v[202:205], v[20:23]
	v_mfma_f32_16x16x32_bf16 v[16:19], v[178:181], v[202:205], v[16:19]
	v_mfma_f32_16x16x32_bf16 v[4:7], v[170:173], v[210:213], v[4:7]
	v_mfma_f32_16x16x32_bf16 v[0:3], v[178:181], v[210:213], v[0:3]
	v_mfma_f32_16x16x32_bf16 v[60:63], v[214:217], v[182:185], v[60:63]
	v_mfma_f32_16x16x32_bf16 v[56:59], v[222:225], v[182:185], v[56:59]
	v_mfma_f32_16x16x32_bf16 v[44:47], v[214:217], v[190:193], v[44:47]
	v_mfma_f32_16x16x32_bf16 v[40:43], v[222:225], v[190:193], v[40:43]
	v_mfma_f32_16x16x32_bf16 v[28:31], v[214:217], v[198:201], v[28:31]
	v_mfma_f32_16x16x32_bf16 v[24:27], v[222:225], v[198:201], v[24:27]
	v_mfma_f32_16x16x32_bf16 v[12:15], v[214:217], v[206:209], v[12:15]
	v_mfma_f32_16x16x32_bf16 v[8:11], v[222:225], v[206:209], v[8:11]
	v_mfma_f32_16x16x32_bf16 v[60:63], v[218:221], v[186:189], v[60:63]
	v_mfma_f32_16x16x32_bf16 v[56:59], v[226:229], v[186:189], v[56:59]
	v_mfma_f32_16x16x32_bf16 v[44:47], v[218:221], v[194:197], v[44:47]
	v_mfma_f32_16x16x32_bf16 v[40:43], v[226:229], v[194:197], v[40:43]
	v_mfma_f32_16x16x32_bf16 v[28:31], v[218:221], v[202:205], v[28:31]
	v_mfma_f32_16x16x32_bf16 v[24:27], v[226:229], v[202:205], v[24:27]
	v_mfma_f32_16x16x32_bf16 v[12:15], v[218:221], v[210:213], v[12:15]
	v_mfma_f32_16x16x32_bf16 v[8:11], v[226:229], v[210:213], v[8:11]
	s_setprio 0
	s_add_i32 s20, 16, 0x18000
	v_add_u32_e32 v138, s20, v156
	s_barrier
	ds_read_b128 v[166:169], v138
	ds_read_b128 v[170:173], v138 offset:1024
	ds_read_b128 v[174:177], v138 offset:2048
	ds_read_b128 v[178:181], v138 offset:3072
	s_add_u32 s18, s18, 0x40000
	s_addc_u32 s19, s19, 0
	s_mov_b32 m0, s36
	v_lshl_add_u64 v[214:215], s[18:19], 0, v[148:149]
	ds_read_b128 v[182:185], v158 offset:32768
	ds_read_b128 v[186:189], v158 offset:33792
	ds_read_b128 v[190:193], v158 offset:34816
	ds_read_b128 v[194:197], v158 offset:35840
	ds_read_b128 v[198:201], v158 offset:36864
	ds_read_b128 v[202:205], v158 offset:37888
	ds_read_b128 v[206:209], v158 offset:38912
	ds_read_b128 v[210:213], v158 offset:39936
	global_load_lds_dwordx4 v[214:215], off
	v_lshl_add_u64 v[214:215], s[18:19], 0, v[146:147]
	s_mov_b32 m0, s37
	s_nop 0
	global_load_lds_dwordx4 v[214:215], off
	s_add_i32 s18, 16, 0x1c000
	v_add_u32_e32 v138, s18, v156
	ds_read_b128 v[214:217], v138
	ds_read_b128 v[218:221], v138 offset:1024
	ds_read_b128 v[222:225], v138 offset:2048
	ds_read_b128 v[226:229], v138 offset:3072
	s_waitcnt vmcnt(8) lgkmcnt(0)
	s_barrier
	s_setprio 1
	v_mfma_f32_16x16x32_bf16 v[116:119], v[166:169], v[182:185], v[116:119]
	v_mfma_f32_16x16x32_bf16 v[112:115], v[174:177], v[182:185], v[112:115]
	v_mfma_f32_16x16x32_bf16 v[100:103], v[166:169], v[190:193], v[100:103]
	v_mfma_f32_16x16x32_bf16 v[96:99], v[174:177], v[190:193], v[96:99]
	v_mfma_f32_16x16x32_bf16 v[84:87], v[166:169], v[198:201], v[84:87]
	v_mfma_f32_16x16x32_bf16 v[80:83], v[174:177], v[198:201], v[80:83]
	v_mfma_f32_16x16x32_bf16 v[68:71], v[166:169], v[206:209], v[68:71]
	v_mfma_f32_16x16x32_bf16 v[64:67], v[174:177], v[206:209], v[64:67]
	v_mfma_f32_16x16x32_bf16 v[116:119], v[170:173], v[186:189], v[116:119]
	v_mfma_f32_16x16x32_bf16 v[112:115], v[178:181], v[186:189], v[112:115]
	v_mfma_f32_16x16x32_bf16 v[100:103], v[170:173], v[194:197], v[100:103]
	v_mfma_f32_16x16x32_bf16 v[96:99], v[178:181], v[194:197], v[96:99]
	v_mfma_f32_16x16x32_bf16 v[84:87], v[170:173], v[202:205], v[84:87]
	v_mfma_f32_16x16x32_bf16 v[80:83], v[178:181], v[202:205], v[80:83]
	v_mfma_f32_16x16x32_bf16 v[68:71], v[170:173], v[210:213], v[68:71]
	v_mfma_f32_16x16x32_bf16 v[64:67], v[178:181], v[210:213], v[64:67]
	v_mfma_f32_16x16x32_bf16 v[124:127], v[214:217], v[182:185], v[124:127]
	v_mfma_f32_16x16x32_bf16 v[120:123], v[222:225], v[182:185], v[120:123]
	v_mfma_f32_16x16x32_bf16 v[108:111], v[214:217], v[190:193], v[108:111]
	v_mfma_f32_16x16x32_bf16 v[104:107], v[222:225], v[190:193], v[104:107]
	v_mfma_f32_16x16x32_bf16 v[92:95], v[214:217], v[198:201], v[92:95]
	v_mfma_f32_16x16x32_bf16 v[88:91], v[222:225], v[198:201], v[88:91]
	v_mfma_f32_16x16x32_bf16 v[76:79], v[214:217], v[206:209], v[76:79]
	v_mfma_f32_16x16x32_bf16 v[72:75], v[222:225], v[206:209], v[72:75]
	v_mfma_f32_16x16x32_bf16 v[124:127], v[218:221], v[186:189], v[124:127]
	v_mfma_f32_16x16x32_bf16 v[120:123], v[226:229], v[186:189], v[120:123]
	v_mfma_f32_16x16x32_bf16 v[108:111], v[218:221], v[194:197], v[108:111]
	v_mfma_f32_16x16x32_bf16 v[104:107], v[226:229], v[194:197], v[104:107]
	v_mfma_f32_16x16x32_bf16 v[92:95], v[218:221], v[202:205], v[92:95]
	v_mfma_f32_16x16x32_bf16 v[88:91], v[226:229], v[202:205], v[88:91]
	v_mfma_f32_16x16x32_bf16 v[76:79], v[218:221], v[210:213], v[76:79]
	v_mfma_f32_16x16x32_bf16 v[72:75], v[226:229], v[210:213], v[72:75]
	s_setprio 0
	s_barrier
	ds_read_b128 v[182:185], v158 offset:49152
	ds_read_b128 v[186:189], v158 offset:50176
	ds_read_b128 v[190:193], v158 offset:51200
	ds_read_b128 v[194:197], v158 offset:52224
	ds_read_b128 v[198:201], v158 offset:53248
	ds_read_b128 v[202:205], v158 offset:54272
	ds_read_b128 v[206:209], v158 offset:55296
	ds_read_b128 v[210:213], v158 offset:56320
	s_add_i32 s19, s20, s5
	v_lshl_add_u64 v[130:131], v[130:131], 0, s[28:29]
	s_mov_b32 m0, s19
	s_nop 0
	global_load_lds_dwordx4 v[130:131], off
	v_lshl_add_u64 v[130:131], v[132:133], 0, s[28:29]
	s_add_i32 m0, s19, 0x2000
	s_nop 0
	global_load_lds_dwordx4 v[130:131], off
	s_mov_b32 m0, s44
	v_lshl_add_u64 v[130:131], v[134:135], 0, s[28:29]
	global_load_lds_dwordx4 v[130:131], off
	v_lshl_add_u64 v[130:131], v[136:137], 0, s[28:29]
	s_mov_b32 m0, s45
	s_nop 0
	global_load_lds_dwordx4 v[130:131], off
	s_add_u32 s14, s14, 0x40080
	s_addc_u32 s15, s15, 0
	s_add_i32 s18, s18, s5
	v_lshl_add_u64 v[130:131], s[14:15], 0, v[128:129]
	s_mov_b32 m0, s18
	s_nop 0
	global_load_lds_dwordx4 v[130:131], off
	v_lshl_add_u64 v[130:131], s[14:15], 0, v[144:145]
	s_add_i32 m0, s18, 0x2000
	s_nop 0
	global_load_lds_dwordx4 v[130:131], off
	s_waitcnt vmcnt(8) lgkmcnt(0)
	s_barrier
	s_setprio 1
	v_mfma_f32_16x16x32_bf16 v[52:55], v[166:169], v[182:185], v[52:55]
	v_mfma_f32_16x16x32_bf16 v[48:51], v[174:177], v[182:185], v[48:51]
	v_mfma_f32_16x16x32_bf16 v[36:39], v[166:169], v[190:193], v[36:39]
	v_mfma_f32_16x16x32_bf16 v[32:35], v[174:177], v[190:193], v[32:35]
	v_mfma_f32_16x16x32_bf16 v[20:23], v[166:169], v[198:201], v[20:23]
	v_mfma_f32_16x16x32_bf16 v[16:19], v[174:177], v[198:201], v[16:19]
	v_mfma_f32_16x16x32_bf16 v[4:7], v[166:169], v[206:209], v[4:7]
	v_mfma_f32_16x16x32_bf16 v[0:3], v[174:177], v[206:209], v[0:3]
	v_mfma_f32_16x16x32_bf16 v[52:55], v[170:173], v[186:189], v[52:55]
	v_mfma_f32_16x16x32_bf16 v[48:51], v[178:181], v[186:189], v[48:51]
	v_mfma_f32_16x16x32_bf16 v[36:39], v[170:173], v[194:197], v[36:39]
	v_mfma_f32_16x16x32_bf16 v[32:35], v[178:181], v[194:197], v[32:35]
	v_mfma_f32_16x16x32_bf16 v[20:23], v[170:173], v[202:205], v[20:23]
	v_mfma_f32_16x16x32_bf16 v[16:19], v[178:181], v[202:205], v[16:19]
	v_mfma_f32_16x16x32_bf16 v[4:7], v[170:173], v[210:213], v[4:7]
	v_mfma_f32_16x16x32_bf16 v[0:3], v[178:181], v[210:213], v[0:3]
	v_mfma_f32_16x16x32_bf16 v[60:63], v[214:217], v[182:185], v[60:63]
	v_mfma_f32_16x16x32_bf16 v[56:59], v[222:225], v[182:185], v[56:59]
	v_mfma_f32_16x16x32_bf16 v[44:47], v[214:217], v[190:193], v[44:47]
	v_mfma_f32_16x16x32_bf16 v[40:43], v[222:225], v[190:193], v[40:43]
	v_mfma_f32_16x16x32_bf16 v[28:31], v[214:217], v[198:201], v[28:31]
	v_mfma_f32_16x16x32_bf16 v[24:27], v[222:225], v[198:201], v[24:27]
	v_mfma_f32_16x16x32_bf16 v[12:15], v[214:217], v[206:209], v[12:15]
	v_mfma_f32_16x16x32_bf16 v[8:11], v[222:225], v[206:209], v[8:11]
	v_mfma_f32_16x16x32_bf16 v[60:63], v[218:221], v[186:189], v[60:63]
	v_mfma_f32_16x16x32_bf16 v[56:59], v[226:229], v[186:189], v[56:59]
	v_mfma_f32_16x16x32_bf16 v[44:47], v[218:221], v[194:197], v[44:47]
	v_mfma_f32_16x16x32_bf16 v[40:43], v[226:229], v[194:197], v[40:43]
	v_mfma_f32_16x16x32_bf16 v[28:31], v[218:221], v[202:205], v[28:31]
	v_mfma_f32_16x16x32_bf16 v[24:27], v[226:229], v[202:205], v[24:27]
	v_mfma_f32_16x16x32_bf16 v[12:15], v[218:221], v[210:213], v[12:15]
	v_mfma_f32_16x16x32_bf16 v[8:11], v[226:229], v[210:213], v[8:11]
	s_setprio 0
	s_add_i32 s92, s92, 2
	s_add_u32 s30, s30, 0x100
	s_addc_u32 s31, s31, 0
	s_add_u32 s25, s25, 0x100
	s_addc_u32 s47, s47, 0
	s_cmp_gt_u32 s92, 13
	s_cbranch_scc1 .Lg1_exit
	s_barrier
	s_branch .LBB0_391
